# leading wave half takes its pairing barrier about one MFMA slot into its epilogue instead of at its start
# baseline (speedup 1.0000x reference)
.LBB0_200:
	s_cmpk_gt_u32 s8, 0xff
	s_cbranch_scc1 .Lepi0_proj0
	s_barrier

.LBB0_271:
	v_mov_b32_e32 v158, v111
	v_mov_b32_e32 v159, v127
	v_mov_b32_e32 v156, v110
	v_mov_b32_e32 v157, v126
	v_pk_mul_f32 v[158:159], v[158:159], v[158:159]
	v_pk_mul_f32 v[224:225], v[118:119], v[118:119]
	v_pk_fma_f32 v[156:157], v[156:157], v[156:157], v[158:159]
	v_mov_b32_e32 v158, v112
	v_mov_b32_e32 v159, v128
	v_pk_fma_f32 v[156:157], v[158:159], v[158:159], v[156:157]
	v_mov_b32_e32 v158, v113
	v_mov_b32_e32 v159, v129
	v_pk_fma_f32 v[156:157], v[158:159], v[158:159], v[156:157]
	v_mov_b32_e32 v158, v106
	v_mov_b32_e32 v159, v122
	v_pk_fma_f32 v[156:157], v[158:159], v[158:159], v[156:157]
	v_mov_b32_e32 v158, v107
	v_mov_b32_e32 v159, v123
	v_pk_fma_f32 v[156:157], v[158:159], v[158:159], v[156:157]
	v_mov_b32_e32 v158, v108
	v_mov_b32_e32 v159, v124
	v_pk_mul_f32 v[172:173], v[102:103], v[102:103]
	v_pk_fma_f32 v[156:157], v[158:159], v[158:159], v[156:157]
	v_mov_b32_e32 v158, v109
	v_mov_b32_e32 v159, v125
	v_pk_fma_f32 v[156:157], v[158:159], v[158:159], v[156:157]
	v_mov_b32_e32 v158, v172
	v_mov_b32_e32 v159, v224
	v_pk_add_f32 v[240:241], v[156:157], v[158:159]
	v_mov_b32_e32 v158, v79
	v_mov_b32_e32 v159, v95
	v_mov_b32_e32 v156, v78
	v_mov_b32_e32 v157, v94
	v_pk_mul_f32 v[158:159], v[158:159], v[158:159]
	v_mov_b32_e32 v170, v15
	v_pk_fma_f32 v[156:157], v[156:157], v[156:157], v[158:159]
	v_mov_b32_e32 v158, v80
	v_mov_b32_e32 v159, v96
	v_pk_fma_f32 v[156:157], v[158:159], v[158:159], v[156:157]
	v_mov_b32_e32 v158, v81
	v_mov_b32_e32 v159, v97
	v_pk_fma_f32 v[156:157], v[158:159], v[158:159], v[156:157]
	v_mov_b32_e32 v158, v74
	v_mov_b32_e32 v159, v90
	v_pk_fma_f32 v[156:157], v[158:159], v[158:159], v[156:157]
	v_mov_b32_e32 v158, v75
	v_mov_b32_e32 v159, v91
	v_mov_b32_e32 v171, v31
	v_pk_fma_f32 v[156:157], v[158:159], v[158:159], v[156:157]
	v_mov_b32_e32 v158, v76
	v_mov_b32_e32 v159, v92
	v_mov_b32_e32 v168, v14
	v_mov_b32_e32 v169, v30
	v_pk_mul_f32 v[170:171], v[170:171], v[170:171]
	v_pk_mul_f32 v[206:207], v[86:87], v[86:87]
	v_pk_mul_f32 v[210:211], v[70:71], v[70:71]
	v_pk_fma_f32 v[156:157], v[158:159], v[158:159], v[156:157]
	v_mov_b32_e32 v158, v77
	v_mov_b32_e32 v159, v93
	v_pk_fma_f32 v[168:169], v[168:169], v[168:169], v[170:171]
	v_mov_b32_e32 v170, v16
	v_mov_b32_e32 v171, v32
	v_pk_fma_f32 v[156:157], v[158:159], v[158:159], v[156:157]
	s_cmpk_gt_u32 s8, 0xff
	s_cbranch_scc1 .Lepi0_proj1
	s_barrier
.Lepi0_proj1:
	v_mov_b32_e32 v158, v210
	v_mov_b32_e32 v159, v206
	v_pk_fma_f32 v[168:169], v[170:171], v[170:171], v[168:169]
	v_mov_b32_e32 v170, v17
	v_mov_b32_e32 v171, v33
	v_pk_add_f32 v[216:217], v[156:157], v[158:159]
	v_mov_b32_e32 v158, v47
	v_mov_b32_e32 v159, v63
	v_pk_fma_f32 v[168:169], v[170:171], v[170:171], v[168:169]
	v_mov_b32_e32 v170, v10
	v_mov_b32_e32 v171, v26
	v_pk_mul_f32 v[220:221], v[120:121], v[120:121]
	v_pk_mul_f32 v[222:223], v[104:105], v[104:105]
	v_mov_b32_e32 v156, v46
	v_mov_b32_e32 v157, v62
	v_pk_mul_f32 v[158:159], v[158:159], v[158:159]
	v_pk_fma_f32 v[168:169], v[170:171], v[170:171], v[168:169]
	v_mov_b32_e32 v170, v11
	v_mov_b32_e32 v171, v27
	v_mov_b32_e32 v224, v173
	v_pk_fma_f32 v[156:157], v[156:157], v[156:157], v[158:159]
	v_mov_b32_e32 v158, v48
	v_mov_b32_e32 v159, v64
	v_pk_fma_f32 v[168:169], v[170:171], v[170:171], v[168:169]
	v_mov_b32_e32 v170, v12
	v_mov_b32_e32 v171, v28
	v_pk_add_f32 v[224:225], v[224:225], v[240:241]
	v_mov_b32_e32 v240, v222
	v_mov_b32_e32 v241, v220
	v_pk_mul_f32 v[218:219], v[114:115], v[114:115]
	v_pk_mul_f32 v[180:181], v[98:99], v[98:99]
	v_pk_fma_f32 v[156:157], v[158:159], v[158:159], v[156:157]
	v_mov_b32_e32 v158, v49
	v_mov_b32_e32 v159, v65
	v_pk_mul_f32 v[162:163], v[22:23], v[22:23]
	v_pk_fma_f32 v[168:169], v[170:171], v[170:171], v[168:169]
	v_mov_b32_e32 v170, v13
	v_mov_b32_e32 v171, v29
	v_pk_add_f32 v[224:225], v[240:241], v[224:225]
	v_mov_b32_e32 v220, v223
	v_lshl_add_u32 v0, s1, 2, v179
	v_pk_fma_f32 v[156:157], v[158:159], v[158:159], v[156:157]
	v_mov_b32_e32 v158, v42
	v_mov_b32_e32 v159, v58
	v_pk_fma_f32 v[168:169], v[170:171], v[170:171], v[168:169]
	v_mov_b32_e32 v171, v162
	v_and_b32_e32 v162, 64, v229
	v_pk_add_f32 v[220:221], v[220:221], v[224:225]
	v_mov_b32_e32 v222, v180
	v_mov_b32_e32 v223, v218
	ds_read_b128 v[142:145], v0
	ds_read_b128 v[138:141], v0 offset:16
	ds_read_b128 v[134:137], v0 offset:128
	ds_read_b128 v[130:133], v0 offset:144
	v_pk_mul_f32 v[190:191], v[116:117], v[116:117]
	v_pk_mul_f32 v[226:227], v[100:101], v[100:101]
	v_pk_fma_f32 v[156:157], v[158:159], v[158:159], v[156:157]
	v_mov_b32_e32 v158, v43
	v_mov_b32_e32 v159, v59
	v_xor_b32_e32 v0, 16, v229
	v_add_u32_e32 v162, 64, v162
	v_pk_add_f32 v[220:221], v[222:223], v[220:221]
	v_mov_b32_e32 v218, v181
	v_pk_fma_f32 v[156:157], v[158:159], v[158:159], v[156:157]
	v_mov_b32_e32 v158, v44
	v_mov_b32_e32 v159, v60
	v_cmp_lt_i32_e32 vcc, v0, v162
	v_pk_add_f32 v[180:181], v[218:219], v[220:221]
	v_mov_b32_e32 v218, v226
	v_mov_b32_e32 v219, v190
	v_pk_mul_f32 v[192:193], v[38:39], v[38:39]
	v_pk_fma_f32 v[156:157], v[158:159], v[158:159], v[156:157]
	v_mov_b32_e32 v158, v45
	v_mov_b32_e32 v159, v61
	v_cndmask_b32_e32 v0, v229, v0, vcc
	v_pk_add_f32 v[180:181], v[218:219], v[180:181]
	v_mov_b32_e32 v190, v227
	v_pk_fma_f32 v[156:157], v[158:159], v[158:159], v[156:157]
	v_mov_b32_e32 v158, v192
	v_lshlrev_b32_e32 v192, 2, v0
	v_pk_add_f32 v[180:181], v[190:191], v[180:181]
	ds_bpermute_b32 v191, v192, v181
	ds_bpermute_b32 v190, v192, v180
	v_xor_b32_e32 v0, 32, v229
	v_cmp_lt_i32_e32 vcc, v0, v162
	s_mov_b32 s6, 0x358637bd
	s_lshl_b32 s1, s38, 8
	v_cndmask_b32_e32 v0, v229, v0, vcc
	v_lshlrev_b32_e32 v210, 2, v0
	s_waitcnt lgkmcnt(0)
	v_pk_add_f32 v[180:181], v[180:181], v[190:191]
	ds_bpermute_b32 v191, v210, v181
	ds_bpermute_b32 v190, v210, v180
	s_add_i32 s2, s1, s17
	s_ashr_i32 s2, s2, 8
	s_mul_i32 s2, s2, 38
	s_add_i32 s2, s2, s72
	s_waitcnt lgkmcnt(0)
	v_pk_add_f32 v[180:181], v[180:181], v[190:191]
	v_mov_b64_e32 v[190:191], s[6:7]
	v_pk_fma_f32 v[180:181], v[180:181], s[26:27], v[190:191] op_sel_hi:[1,0,0]
	v_pk_mul_f32 v[166:167], v[6:7], v[6:7]
	v_mul_f32_e32 v162, 0x4b800000, v181
	v_cmp_gt_f32_e32 vcc, s95, v181
	s_ashr_i32 s3, s2, 31
	v_mov_b32_e32 v170, v166
	v_cndmask_b32_e32 v162, v181, v162, vcc
	v_rsq_f32_e32 v162, v162
	v_and_b32_e32 v166, 0xd8, v228
	s_lshl_b64 s[2:3], s[2:3], 17
	v_or_b32_e32 v0, v166, v244
	v_mul_f32_e32 v181, 0x45800000, v162
	v_cndmask_b32_e32 v162, v162, v181, vcc
	v_mul_f32_e32 v162, v154, v162
	v_pk_mul_f32 v[118:119], v[118:119], v[162:163] op_sel_hi:[1,0]
	v_pk_mul_f32 v[120:121], v[120:121], v[162:163] op_sel_hi:[1,0]
	v_pk_mul_f32 v[118:119], v[134:135], v[118:119]
	v_pk_mul_f32 v[120:121], v[136:137], v[120:121]
	v_pk_mul_f32 v[122:123], v[122:123], v[162:163] op_sel_hi:[1,0]
	v_cvt_pk_bf16_f32 v118, v118, v119
	v_cvt_pk_bf16_f32 v119, v120, v121
	v_mul_f32_e32 v121, 0x4b800000, v180
	v_cmp_gt_f32_e32 vcc, s95, v180
	v_pk_mul_f32 v[122:123], v[138:139], v[122:123]
	v_pk_mul_f32 v[114:115], v[114:115], v[162:163] op_sel_hi:[1,0]
	v_cndmask_b32_e32 v121, v180, v121, vcc
	v_pk_mul_f32 v[220:221], v[130:131], v[114:115]
	v_pk_mul_f32 v[114:115], v[116:117], v[162:163] op_sel_hi:[1,0]
	v_cvt_pk_bf16_f32 v116, v122, v123
	v_rsq_f32_e32 v122, v121
	v_pk_mul_f32 v[126:127], v[126:127], v[162:163] op_sel_hi:[1,0]
	v_pk_mul_f32 v[128:129], v[128:129], v[162:163] op_sel_hi:[1,0]
	v_pk_mul_f32 v[124:125], v[124:125], v[162:163] op_sel_hi:[1,0]
	s_add_u32 s2, s46, s2
	v_pk_mul_f32 v[126:127], v[142:143], v[126:127]
	v_pk_mul_f32 v[128:129], v[144:145], v[128:129]
	v_pk_mul_f32 v[124:125], v[140:141], v[124:125]
	s_addc_u32 s3, s47, s3
	v_lshlrev_b32_e32 v0, 1, v0
	v_pk_mul_f32 v[222:223], v[132:133], v[114:115]
	v_cvt_pk_bf16_f32 v114, v126, v127
	v_cvt_pk_bf16_f32 v115, v128, v129
	v_cvt_pk_bf16_f32 v117, v124, v125
	v_lshl_add_u64 v[218:219], s[2:3], 0, v[0:1]
	v_cvt_pk_bf16_f32 v120, v220, v221
	v_cvt_pk_bf16_f32 v121, v222, v223
	global_store_dwordx4 v0, v[114:117], s[2:3] nt
	global_store_dwordx4 v0, v[118:121], s[2:3] offset:64 nt
	v_mul_f32_e32 v0, 0x45800000, v122
	v_cndmask_b32_e32 v0, v122, v0, vcc
	v_mul_f32_e32 v0, v154, v0
	v_pk_mul_f32 v[98:99], v[98:99], v[0:1] op_sel_hi:[1,0]
	v_pk_mul_f32 v[204:205], v[88:89], v[88:89]
	v_pk_mul_f32 v[208:209], v[72:73], v[72:73]
	v_pk_mul_f32 v[114:115], v[130:131], v[98:99]
	v_pk_mul_f32 v[98:99], v[100:101], v[0:1] op_sel_hi:[1,0]
	v_mov_b32_e32 v206, v211
	v_pk_mul_f32 v[116:117], v[132:133], v[98:99]
	v_pk_add_f32 v[98:99], v[206:207], v[216:217]
	v_mov_b32_e32 v100, v208
	v_mov_b32_e32 v101, v204
	v_pk_mul_f32 v[202:203], v[82:83], v[82:83]
	v_pk_mul_f32 v[214:215], v[66:67], v[66:67]
	v_pk_add_f32 v[98:99], v[100:101], v[98:99]
	v_mov_b32_e32 v204, v209
	v_pk_add_f32 v[98:99], v[204:205], v[98:99]
	v_mov_b32_e32 v100, v214
	v_mov_b32_e32 v101, v202
	v_pk_mul_f32 v[200:201], v[84:85], v[84:85]
	v_pk_mul_f32 v[212:213], v[68:69], v[68:69]
	v_pk_add_f32 v[98:99], v[100:101], v[98:99]
	v_mov_b32_e32 v202, v215
	v_pk_add_f32 v[98:99], v[202:203], v[98:99]
	v_mov_b32_e32 v100, v212
	v_mov_b32_e32 v101, v200
	v_pk_add_f32 v[98:99], v[100:101], v[98:99]
	v_mov_b32_e32 v200, v213
	v_pk_add_f32 v[118:119], v[200:201], v[98:99]
	ds_bpermute_b32 v121, v192, v119
	ds_bpermute_b32 v120, v192, v118
	v_pk_mul_f32 v[106:107], v[106:107], v[0:1] op_sel_hi:[1,0]
	v_pk_mul_f32 v[108:109], v[108:109], v[0:1] op_sel_hi:[1,0]
	v_pk_mul_f32 v[106:107], v[138:139], v[106:107]
	v_pk_mul_f32 v[108:109], v[140:141], v[108:109]
	v_cvt_pk_bf16_f32 v100, v106, v107
	s_waitcnt lgkmcnt(0)
	v_pk_add_f32 v[106:107], v[118:119], v[120:121]
	v_cvt_pk_bf16_f32 v101, v108, v109
	ds_bpermute_b32 v109, v210, v107
	ds_bpermute_b32 v108, v210, v106
	v_pk_mul_f32 v[110:111], v[110:111], v[0:1] op_sel_hi:[1,0]
	v_pk_mul_f32 v[112:113], v[112:113], v[0:1] op_sel_hi:[1,0]
	v_pk_mul_f32 v[102:103], v[102:103], v[0:1] op_sel_hi:[1,0]
	v_pk_mul_f32 v[104:105], v[104:105], v[0:1] op_sel_hi:[1,0]
	s_waitcnt lgkmcnt(0)
	v_pk_add_f32 v[106:107], v[106:107], v[108:109]
	v_pk_mul_f32 v[110:111], v[142:143], v[110:111]
	v_pk_fma_f32 v[106:107], v[106:107], s[26:27], v[190:191] op_sel_hi:[1,0,0]
	v_pk_mul_f32 v[112:113], v[144:145], v[112:113]
	v_mul_f32_e32 v0, 0x4b800000, v107
	v_cmp_gt_f32_e32 vcc, s95, v107
	v_add_co_u32_e64 v108, s[38:39], s94, v218
	s_nop 0
	v_cndmask_b32_e32 v0, v107, v0, vcc
	v_rsq_f32_e32 v0, v0
	v_pk_mul_f32 v[102:103], v[134:135], v[102:103]
	v_pk_mul_f32 v[104:105], v[136:137], v[104:105]
	v_cvt_pk_bf16_f32 v98, v110, v111
	v_cvt_pk_bf16_f32 v99, v112, v113
	v_addc_co_u32_e64 v109, s[38:39], 0, v219, s[38:39]
	v_cvt_pk_bf16_f32 v102, v102, v103
	v_cvt_pk_bf16_f32 v103, v104, v105
	v_cvt_pk_bf16_f32 v104, v114, v115
	v_cvt_pk_bf16_f32 v105, v116, v117
	global_store_dwordx4 v[108:109], v[98:101], off nt
	global_store_dwordx4 v[108:109], v[102:105], off offset:64 nt
	v_pk_mul_f32 v[186:187], v[54:55], v[54:55]
	v_mul_f32_e32 v98, 0x45800000, v0
	v_cndmask_b32_e32 v0, v0, v98, vcc
	v_mul_f32_e32 v0, v154, v0
	v_pk_mul_f32 v[82:83], v[82:83], v[0:1] op_sel_hi:[1,0]
	v_pk_mul_f32 v[94:95], v[94:95], v[0:1] op_sel_hi:[1,0]
	v_pk_mul_f32 v[96:97], v[96:97], v[0:1] op_sel_hi:[1,0]
	v_pk_mul_f32 v[90:91], v[90:91], v[0:1] op_sel_hi:[1,0]
	v_pk_mul_f32 v[92:93], v[92:93], v[0:1] op_sel_hi:[1,0]
	v_pk_mul_f32 v[86:87], v[86:87], v[0:1] op_sel_hi:[1,0]
	v_pk_mul_f32 v[88:89], v[88:89], v[0:1] op_sel_hi:[1,0]
	v_pk_mul_f32 v[98:99], v[130:131], v[82:83]
	v_pk_mul_f32 v[82:83], v[84:85], v[0:1] op_sel_hi:[1,0]
	v_mul_f32_e32 v0, 0x4b800000, v106
	v_cmp_gt_f32_e32 vcc, s95, v106
	v_pk_mul_f32 v[90:91], v[138:139], v[90:91]
	v_pk_mul_f32 v[94:95], v[142:143], v[94:95]
	v_cndmask_b32_e32 v0, v106, v0, vcc
	v_rsq_f32_e32 v0, v0
	v_pk_mul_f32 v[96:97], v[144:145], v[96:97]
	v_pk_mul_f32 v[92:93], v[140:141], v[92:93]
	v_cvt_pk_bf16_f32 v84, v90, v91
	v_add_co_u32_e64 v90, s[38:39], s43, v218
	v_pk_mul_f32 v[86:87], v[134:135], v[86:87]
	v_pk_mul_f32 v[88:89], v[136:137], v[88:89]
	v_pk_mul_f32 v[100:101], v[132:133], v[82:83]
	v_cvt_pk_bf16_f32 v82, v94, v95
	v_cvt_pk_bf16_f32 v83, v96, v97
	v_cvt_pk_bf16_f32 v85, v92, v93
	v_addc_co_u32_e64 v91, s[38:39], 0, v219, s[38:39]
	v_cvt_pk_bf16_f32 v86, v86, v87
	v_cvt_pk_bf16_f32 v87, v88, v89
	v_cvt_pk_bf16_f32 v88, v98, v99
	v_cvt_pk_bf16_f32 v89, v100, v101
	global_store_dwordx4 v[90:91], v[82:85], off nt
	global_store_dwordx4 v[90:91], v[86:89], off offset:64 nt
	v_mov_b32_e32 v159, v186
	v_mul_f32_e32 v82, 0x45800000, v0
	v_cndmask_b32_e32 v0, v0, v82, vcc
	v_mul_f32_e32 v0, v154, v0
	v_pk_mul_f32 v[78:79], v[78:79], v[0:1] op_sel_hi:[1,0]
	v_pk_mul_f32 v[76:77], v[76:77], v[0:1] op_sel_hi:[1,0]
	v_pk_mul_f32 v[66:67], v[66:67], v[0:1] op_sel_hi:[1,0]
	v_pk_mul_f32 v[184:185], v[56:57], v[56:57]
	v_pk_mul_f32 v[188:189], v[40:41], v[40:41]
	v_pk_add_f32 v[198:199], v[156:157], v[158:159]
	v_pk_mul_f32 v[78:79], v[142:143], v[78:79]
	v_pk_mul_f32 v[76:77], v[140:141], v[76:77]
	v_pk_mul_f32 v[82:83], v[130:131], v[66:67]
	v_pk_mul_f32 v[66:67], v[68:69], v[0:1] op_sel_hi:[1,0]
	v_mov_b32_e32 v186, v193
	v_pk_mul_f32 v[84:85], v[132:133], v[66:67]
	v_cvt_pk_bf16_f32 v66, v78, v79
	v_cvt_pk_bf16_f32 v69, v76, v77
	v_pk_add_f32 v[76:77], v[186:187], v[198:199]
	v_mov_b32_e32 v78, v188
	v_mov_b32_e32 v79, v184
	v_pk_mul_f32 v[176:177], v[50:51], v[50:51]
	v_pk_mul_f32 v[196:197], v[34:35], v[34:35]
	v_pk_add_f32 v[76:77], v[78:79], v[76:77]
	v_mov_b32_e32 v184, v189
	v_pk_add_f32 v[76:77], v[184:185], v[76:77]
	v_mov_b32_e32 v78, v196
	v_mov_b32_e32 v79, v176
	v_pk_mul_f32 v[174:175], v[52:53], v[52:53]
	v_pk_mul_f32 v[194:195], v[36:37], v[36:37]
	v_pk_add_f32 v[76:77], v[78:79], v[76:77]
	v_mov_b32_e32 v176, v197
	v_pk_add_f32 v[76:77], v[176:177], v[76:77]
	v_mov_b32_e32 v78, v194
	v_mov_b32_e32 v79, v174
	v_pk_add_f32 v[76:77], v[78:79], v[76:77]
	v_mov_b32_e32 v174, v195
	v_pk_add_f32 v[76:77], v[174:175], v[76:77]
	ds_bpermute_b32 v79, v192, v77
	ds_bpermute_b32 v78, v192, v76
	v_pk_mul_f32 v[74:75], v[74:75], v[0:1] op_sel_hi:[1,0]
	v_pk_mul_f32 v[80:81], v[80:81], v[0:1] op_sel_hi:[1,0]
	v_pk_mul_f32 v[74:75], v[138:139], v[74:75]
	s_movk_i32 s2, 0x6000
	v_pk_mul_f32 v[80:81], v[144:145], v[80:81]
	v_pk_mul_f32 v[70:71], v[70:71], v[0:1] op_sel_hi:[1,0]
	v_pk_mul_f32 v[72:73], v[72:73], v[0:1] op_sel_hi:[1,0]
	v_cvt_pk_bf16_f32 v68, v74, v75
	v_add_co_u32_e32 v74, vcc, s2, v218
	v_pk_mul_f32 v[70:71], v[134:135], v[70:71]
	v_pk_mul_f32 v[72:73], v[136:137], v[72:73]
	v_cvt_pk_bf16_f32 v67, v80, v81
	v_addc_co_u32_e32 v75, vcc, 0, v219, vcc
	v_cvt_pk_bf16_f32 v70, v70, v71
	v_cvt_pk_bf16_f32 v71, v72, v73
	v_cvt_pk_bf16_f32 v72, v82, v83
	v_cvt_pk_bf16_f32 v73, v84, v85
	global_store_dwordx4 v[74:75], v[66:69], off nt
	global_store_dwordx4 v[74:75], v[70:73], off offset:64 nt
	v_add_u32_e32 v0, s1, v245
	s_waitcnt lgkmcnt(0)
	v_pk_add_f32 v[66:67], v[76:77], v[78:79]
	ds_bpermute_b32 v69, v210, v67
	ds_bpermute_b32 v68, v210, v66
	v_lshrrev_b32_e32 v0, 8, v0
	v_mad_i32_i24 v70, v0, 38, s72
	v_ashrrev_i32_e32 v71, 31, v70
	v_or_b32_e32 v0, v166, v246
	s_waitcnt lgkmcnt(0)
	v_pk_add_f32 v[66:67], v[66:67], v[68:69]
	v_lshlrev_b64 v[70:71], 17, v[70:71]
	v_pk_fma_f32 v[66:67], v[66:67], s[26:27], v[190:191] op_sel_hi:[1,0,0]
	v_lshlrev_b32_e32 v0, 1, v0
	v_mul_f32_e32 v68, 0x4b800000, v67
	v_cmp_gt_f32_e32 vcc, s95, v67
	v_pk_mul_f32 v[160:161], v[24:25], v[24:25]
	v_pk_mul_f32 v[164:165], v[8:9], v[8:9]
	v_cndmask_b32_e32 v67, v67, v68, vcc
	v_rsq_f32_e32 v67, v67
	v_lshl_add_u64 v[68:69], s[46:47], 0, v[70:71]
	v_lshl_add_u64 v[68:69], v[68:69], 0, v[0:1]
	v_pk_add_f32 v[170:171], v[168:169], v[170:171]
	v_mul_f32_e32 v0, 0x45800000, v67
	v_cndmask_b32_e32 v0, v67, v0, vcc
	v_mul_f32_e32 v0, v154, v0
	v_pk_mul_f32 v[50:51], v[50:51], v[0:1] op_sel_hi:[1,0]
	v_pk_mul_f32 v[62:63], v[62:63], v[0:1] op_sel_hi:[1,0]
	v_pk_mul_f32 v[64:65], v[64:65], v[0:1] op_sel_hi:[1,0]
	v_pk_mul_f32 v[58:59], v[58:59], v[0:1] op_sel_hi:[1,0]
	v_pk_mul_f32 v[60:61], v[60:61], v[0:1] op_sel_hi:[1,0]
	v_pk_mul_f32 v[54:55], v[54:55], v[0:1] op_sel_hi:[1,0]
	v_pk_mul_f32 v[56:57], v[56:57], v[0:1] op_sel_hi:[1,0]
	v_pk_mul_f32 v[70:71], v[130:131], v[50:51]
	v_pk_mul_f32 v[50:51], v[52:53], v[0:1] op_sel_hi:[1,0]
	v_mul_f32_e32 v0, 0x4b800000, v66
	v_cmp_gt_f32_e32 vcc, s95, v66
	v_pk_mul_f32 v[62:63], v[142:143], v[62:63]
	v_pk_mul_f32 v[64:65], v[144:145], v[64:65]
	v_cndmask_b32_e32 v0, v66, v0, vcc
	v_rsq_f32_e32 v0, v0
	v_pk_mul_f32 v[58:59], v[138:139], v[58:59]
	v_pk_mul_f32 v[60:61], v[140:141], v[60:61]
	v_pk_mul_f32 v[54:55], v[134:135], v[54:55]
	v_pk_mul_f32 v[56:57], v[136:137], v[56:57]
	v_pk_mul_f32 v[72:73], v[132:133], v[50:51]
	v_cvt_pk_bf16_f32 v50, v62, v63
	v_cvt_pk_bf16_f32 v51, v64, v65
	v_cvt_pk_bf16_f32 v52, v58, v59
	v_cvt_pk_bf16_f32 v53, v60, v61
	v_cvt_pk_bf16_f32 v54, v54, v55
	v_cvt_pk_bf16_f32 v55, v56, v57
	v_cvt_pk_bf16_f32 v56, v70, v71
	v_cvt_pk_bf16_f32 v57, v72, v73
	global_store_dwordx4 v[68:69], v[50:53], off nt
	global_store_dwordx4 v[68:69], v[54:57], off offset:64 nt
	v_mov_b32_e32 v162, v167
	v_mul_f32_e32 v50, 0x45800000, v0
	v_cndmask_b32_e32 v0, v0, v50, vcc
	v_mul_f32_e32 v0, v154, v0
	v_pk_mul_f32 v[42:43], v[42:43], v[0:1] op_sel_hi:[1,0]
	v_pk_mul_f32 v[44:45], v[44:45], v[0:1] op_sel_hi:[1,0]
	v_pk_mul_f32 v[42:43], v[138:139], v[42:43]
	v_pk_mul_f32 v[44:45], v[140:141], v[44:45]
	v_pk_mul_f32 v[34:35], v[34:35], v[0:1] op_sel_hi:[1,0]
	v_pk_mul_f32 v[158:159], v[18:19], v[18:19]
	v_pk_mul_f32 v[50:51], v[130:131], v[34:35]
	v_pk_mul_f32 v[34:35], v[36:37], v[0:1] op_sel_hi:[1,0]
	v_cvt_pk_bf16_f32 v36, v42, v43
	v_cvt_pk_bf16_f32 v37, v44, v45
	v_pk_add_f32 v[42:43], v[162:163], v[170:171]
	v_mov_b32_e32 v44, v164
	v_mov_b32_e32 v45, v160
	v_pk_mul_f32 v[172:173], v[2:3], v[2:3]
	v_pk_add_f32 v[42:43], v[44:45], v[42:43]
	v_mov_b32_e32 v160, v165
	v_pk_add_f32 v[42:43], v[160:161], v[42:43]
	v_mov_b32_e32 v44, v172
	v_mov_b32_e32 v45, v158
	v_pk_mul_f32 v[156:157], v[20:21], v[20:21]
	v_pk_mul_f32 v[168:169], v[4:5], v[4:5]
	v_pk_add_f32 v[42:43], v[44:45], v[42:43]
	v_mov_b32_e32 v158, v173
	v_pk_add_f32 v[42:43], v[158:159], v[42:43]
	v_mov_b32_e32 v44, v168
	v_mov_b32_e32 v45, v156
	v_pk_mul_f32 v[46:47], v[46:47], v[0:1] op_sel_hi:[1,0]
	v_pk_mul_f32 v[48:49], v[48:49], v[0:1] op_sel_hi:[1,0]
	v_pk_mul_f32 v[38:39], v[38:39], v[0:1] op_sel_hi:[1,0]
	v_pk_mul_f32 v[40:41], v[40:41], v[0:1] op_sel_hi:[1,0]
	v_add_u32_e32 v0, s1, v247
	v_pk_add_f32 v[42:43], v[44:45], v[42:43]
	v_mov_b32_e32 v156, v169
	v_lshrrev_b32_e32 v0, 8, v0
	v_pk_add_f32 v[42:43], v[156:157], v[42:43]
	v_pk_mul_f32 v[52:53], v[132:133], v[34:35]
	v_mad_i32_i24 v34, v0, 38, s72
	ds_bpermute_b32 v45, v192, v43
	ds_bpermute_b32 v44, v192, v42
	v_ashrrev_i32_e32 v35, 31, v34
	v_or_b32_e32 v0, v166, v248
	v_lshlrev_b64 v[34:35], 17, v[34:35]
	v_pk_mul_f32 v[46:47], v[142:143], v[46:47]
	v_pk_mul_f32 v[48:49], v[144:145], v[48:49]
	v_lshl_add_u64 v[34:35], s[46:47], 0, v[34:35]
	v_lshlrev_b32_e32 v0, 1, v0
	v_pk_mul_f32 v[38:39], v[134:135], v[38:39]
	v_pk_mul_f32 v[40:41], v[136:137], v[40:41]
	v_lshl_add_u64 v[54:55], v[34:35], 0, v[0:1]
	v_cvt_pk_bf16_f32 v34, v46, v47
	v_cvt_pk_bf16_f32 v35, v48, v49
	v_cvt_pk_bf16_f32 v38, v38, v39
	v_cvt_pk_bf16_f32 v39, v40, v41
	v_cvt_pk_bf16_f32 v40, v50, v51
	v_cvt_pk_bf16_f32 v41, v52, v53
	global_store_dwordx4 v[54:55], v[34:37], off nt
	global_store_dwordx4 v[54:55], v[38:41], off offset:64 nt
	v_add_u32_e32 v0, s1, v249
	s_waitcnt lgkmcnt(0)
	v_pk_add_f32 v[34:35], v[42:43], v[44:45]
	ds_bpermute_b32 v37, v210, v35
	ds_bpermute_b32 v36, v210, v34
	v_lshrrev_b32_e32 v0, 8, v0
	v_mad_i32_i24 v38, v0, 38, s72
	v_ashrrev_i32_e32 v39, 31, v38
	v_or_b32_e32 v0, v166, v250
	s_waitcnt lgkmcnt(0)
	v_pk_add_f32 v[34:35], v[34:35], v[36:37]
	v_lshlrev_b64 v[38:39], 17, v[38:39]
	v_pk_fma_f32 v[34:35], v[34:35], s[26:27], v[190:191] op_sel_hi:[1,0,0]
	v_lshlrev_b32_e32 v0, 1, v0
	v_mul_f32_e32 v36, 0x4b800000, v35
	v_cmp_gt_f32_e32 vcc, s95, v35
	s_nop 1
	v_cndmask_b32_e32 v35, v35, v36, vcc
	v_rsq_f32_e32 v35, v35
	v_lshl_add_u64 v[36:37], s[46:47], 0, v[38:39]
	v_lshl_add_u64 v[36:37], v[36:37], 0, v[0:1]
	v_mul_f32_e32 v0, 0x45800000, v35
	v_cndmask_b32_e32 v0, v35, v0, vcc
	v_mul_f32_e32 v0, v154, v0
	v_pk_mul_f32 v[18:19], v[18:19], v[0:1] op_sel_hi:[1,0]
	v_pk_mul_f32 v[30:31], v[30:31], v[0:1] op_sel_hi:[1,0]
	v_pk_mul_f32 v[32:33], v[32:33], v[0:1] op_sel_hi:[1,0]
	v_pk_mul_f32 v[26:27], v[26:27], v[0:1] op_sel_hi:[1,0]
	v_pk_mul_f32 v[28:29], v[28:29], v[0:1] op_sel_hi:[1,0]
	v_pk_mul_f32 v[22:23], v[22:23], v[0:1] op_sel_hi:[1,0]
	v_pk_mul_f32 v[24:25], v[24:25], v[0:1] op_sel_hi:[1,0]
	v_pk_mul_f32 v[38:39], v[130:131], v[18:19]
	v_pk_mul_f32 v[18:19], v[20:21], v[0:1] op_sel_hi:[1,0]
	v_mul_f32_e32 v0, 0x4b800000, v34
	v_cmp_gt_f32_e32 vcc, s95, v34
	v_pk_mul_f32 v[30:31], v[142:143], v[30:31]
	v_pk_mul_f32 v[32:33], v[144:145], v[32:33]
	v_cndmask_b32_e32 v0, v34, v0, vcc
	v_rsq_f32_e32 v0, v0
	v_pk_mul_f32 v[26:27], v[138:139], v[26:27]
	v_pk_mul_f32 v[28:29], v[140:141], v[28:29]
	v_pk_mul_f32 v[22:23], v[134:135], v[22:23]
	v_pk_mul_f32 v[24:25], v[136:137], v[24:25]
	v_pk_mul_f32 v[40:41], v[132:133], v[18:19]
	v_cvt_pk_bf16_f32 v18, v30, v31
	v_cvt_pk_bf16_f32 v19, v32, v33
	v_cvt_pk_bf16_f32 v20, v26, v27
	v_cvt_pk_bf16_f32 v21, v28, v29
	v_cvt_pk_bf16_f32 v22, v22, v23
	v_cvt_pk_bf16_f32 v23, v24, v25
	v_cvt_pk_bf16_f32 v24, v38, v39
	v_cvt_pk_bf16_f32 v25, v40, v41
	global_store_dwordx4 v[36:37], v[18:21], off nt
	global_store_dwordx4 v[36:37], v[22:25], off offset:64 nt
	s_nop 0
	v_mul_f32_e32 v18, 0x45800000, v0
	v_cndmask_b32_e32 v0, v0, v18, vcc
	v_mul_f32_e32 v0, v154, v0
	v_pk_mul_f32 v[2:3], v[2:3], v[0:1] op_sel_hi:[1,0]
	v_pk_mul_f32 v[14:15], v[14:15], v[0:1] op_sel_hi:[1,0]
	v_pk_mul_f32 v[16:17], v[16:17], v[0:1] op_sel_hi:[1,0]
	v_pk_mul_f32 v[10:11], v[10:11], v[0:1] op_sel_hi:[1,0]
	v_pk_mul_f32 v[12:13], v[12:13], v[0:1] op_sel_hi:[1,0]
	v_pk_mul_f32 v[6:7], v[6:7], v[0:1] op_sel_hi:[1,0]
	v_pk_mul_f32 v[8:9], v[8:9], v[0:1] op_sel_hi:[1,0]
	v_pk_mul_f32 v[18:19], v[130:131], v[2:3]
	v_pk_mul_f32 v[2:3], v[4:5], v[0:1] op_sel_hi:[1,0]
	v_add_u32_e32 v0, s1, v251
	v_lshrrev_b32_e32 v0, 8, v0
	v_pk_mul_f32 v[20:21], v[132:133], v[2:3]
	v_mad_i32_i24 v2, v0, 38, s72
	v_ashrrev_i32_e32 v3, 31, v2
	v_or_b32_e32 v0, v166, v252
	v_lshlrev_b64 v[2:3], 17, v[2:3]
	v_pk_mul_f32 v[14:15], v[142:143], v[14:15]
	v_pk_mul_f32 v[16:17], v[144:145], v[16:17]
	v_pk_mul_f32 v[10:11], v[138:139], v[10:11]
	v_pk_mul_f32 v[12:13], v[140:141], v[12:13]
	v_pk_mul_f32 v[6:7], v[134:135], v[6:7]
	v_pk_mul_f32 v[8:9], v[136:137], v[8:9]
	v_lshl_add_u64 v[2:3], s[46:47], 0, v[2:3]
	v_lshlrev_b32_e32 v0, 1, v0
	v_lshl_add_u64 v[156:157], v[2:3], 0, v[0:1]
	v_cvt_pk_bf16_f32 v2, v14, v15
	v_cvt_pk_bf16_f32 v3, v16, v17
	v_cvt_pk_bf16_f32 v4, v10, v11
	v_cvt_pk_bf16_f32 v5, v12, v13
	v_cvt_pk_bf16_f32 v130, v6, v7
	v_cvt_pk_bf16_f32 v131, v8, v9
	v_cvt_pk_bf16_f32 v132, v18, v19
	v_cvt_pk_bf16_f32 v133, v20, v21
	global_store_dwordx4 v[156:157], v[2:5], off nt
	s_branch .LBB0_175

.Lepix_branch:
	s_branch .LBB0_521
	s_nop 0
	s_nop 0
	s_nop 0
	s_nop 0
	s_nop 0
	s_nop 0
	s_nop 0
	s_nop 0
	s_nop 0
	s_nop 0
	s_nop 0
.LBB0_520:
	s_waitcnt vmcnt(0)
	v_lshlrev_b32_e32 v68, 16, v62
	v_and_b32_e32 v69, 0xffff0000, v62
	v_lshlrev_b32_e32 v62, 16, v63
	v_and_b32_e32 v63, 0xffff0000, v63
	v_pk_mul_f32 v[68:69], v[174:175], v[68:69]
	v_lshlrev_b32_e32 v70, 16, v58
	v_and_b32_e32 v71, 0xffff0000, v58
	v_pk_mul_f32 v[62:63], v[174:175], v[62:63]
	v_lshlrev_b32_e32 v58, 16, v59
	v_and_b32_e32 v59, 0xffff0000, v59
	v_pk_fma_f32 v[30:31], v[30:31], v[70:71], v[68:69]
	v_pk_fma_f32 v[32:33], v[32:33], v[58:59], v[62:63]
	v_cvt_pk_bf16_f32 v30, v30, v31
	v_cvt_pk_bf16_f32 v31, v32, v33
	v_lshlrev_b32_e32 v32, 16, v64
	v_and_b32_e32 v33, 0xffff0000, v64
	v_pk_mul_f32 v[32:33], v[174:175], v[32:33]
	v_lshlrev_b32_e32 v58, 16, v60
	v_and_b32_e32 v59, 0xffff0000, v60
	v_pk_fma_f32 v[26:27], v[26:27], v[58:59], v[32:33]
	v_lshlrev_b32_e32 v58, 16, v61
	v_cvt_pk_bf16_f32 v32, v26, v27
	v_lshlrev_b32_e32 v26, 16, v65
	v_and_b32_e32 v27, 0xffff0000, v65
	v_pk_mul_f32 v[26:27], v[174:175], v[26:27]
	v_and_b32_e32 v59, 0xffff0000, v61
	v_pk_fma_f32 v[26:27], v[28:29], v[58:59], v[26:27]
	v_lshlrev_b32_e32 v28, 16, v46
	v_cvt_pk_bf16_f32 v33, v26, v27
	v_lshlrev_b32_e32 v26, 16, v50
	v_and_b32_e32 v27, 0xffff0000, v50
	v_pk_mul_f32 v[26:27], v[174:175], v[26:27]
	v_and_b32_e32 v29, 0xffff0000, v46
	v_pk_fma_f32 v[22:23], v[22:23], v[28:29], v[26:27]
	v_lshlrev_b32_e32 v26, 16, v51
	v_and_b32_e32 v27, 0xffff0000, v51
	v_pk_mul_f32 v[26:27], v[174:175], v[26:27]
	v_lshlrev_b32_e32 v28, 16, v47
	v_and_b32_e32 v29, 0xffff0000, v47
	v_pk_fma_f32 v[24:25], v[24:25], v[28:29], v[26:27]
	v_cvt_pk_bf16_f32 v22, v22, v23
	v_cvt_pk_bf16_f32 v23, v24, v25
	v_lshlrev_b32_e32 v24, 16, v52
	v_and_b32_e32 v25, 0xffff0000, v52
	v_pk_mul_f32 v[24:25], v[174:175], v[24:25]
	v_lshlrev_b32_e32 v26, 16, v48
	v_and_b32_e32 v27, 0xffff0000, v48
	v_add_u32_e32 v66, 0xa0, v170
	v_pk_fma_f32 v[18:19], v[18:19], v[26:27], v[24:25]
	v_ashrrev_i32_e32 v67, 31, v66
	v_cvt_pk_bf16_f32 v24, v18, v19
	v_lshlrev_b32_e32 v18, 16, v53
	v_and_b32_e32 v19, 0xffff0000, v53
	v_lshlrev_b64 v[66:67], 11, v[66:67]
	v_pk_mul_f32 v[18:19], v[174:175], v[18:19]
	v_lshlrev_b32_e32 v26, 16, v49
	v_and_b32_e32 v27, 0xffff0000, v49
	v_lshl_add_u64 v[66:67], s[0:1], 0, v[66:67]
	v_mov_b32_e32 v173, v1
	v_pk_fma_f32 v[18:19], v[20:21], v[26:27], v[18:19]
	v_lshl_add_u64 v[66:67], v[66:67], 0, v[172:173]
	v_cvt_pk_bf16_f32 v25, v18, v19
	v_lshlrev_b32_e32 v20, 16, v54
	v_and_b32_e32 v21, 0xffff0000, v54
	global_store_dwordx4 v[66:67], v[22:25], off offset:64
	v_pk_mul_f32 v[20:21], v[174:175], v[20:21]
	v_add_u32_e32 v18, 0xb0, v170
	v_lshlrev_b32_e32 v22, 16, v42
	v_and_b32_e32 v23, 0xffff0000, v42
	v_pk_fma_f32 v[14:15], v[14:15], v[22:23], v[20:21]
	v_lshlrev_b32_e32 v20, 16, v55
	v_and_b32_e32 v21, 0xffff0000, v55
	v_pk_mul_f32 v[20:21], v[174:175], v[20:21]
	v_lshlrev_b32_e32 v22, 16, v43
	v_and_b32_e32 v23, 0xffff0000, v43
	v_pk_fma_f32 v[16:17], v[16:17], v[22:23], v[20:21]
	v_cvt_pk_bf16_f32 v14, v14, v15
	v_cvt_pk_bf16_f32 v15, v16, v17
	v_lshlrev_b32_e32 v16, 16, v56
	v_and_b32_e32 v17, 0xffff0000, v56
	v_pk_mul_f32 v[16:17], v[174:175], v[16:17]
	v_lshlrev_b32_e32 v20, 16, v44
	v_and_b32_e32 v21, 0xffff0000, v44
	v_pk_fma_f32 v[10:11], v[10:11], v[20:21], v[16:17]
	v_lshlrev_b32_e32 v20, 16, v45
	v_cvt_pk_bf16_f32 v16, v10, v11
	v_lshlrev_b32_e32 v10, 16, v57
	v_and_b32_e32 v11, 0xffff0000, v57
	v_pk_mul_f32 v[10:11], v[174:175], v[10:11]
	v_and_b32_e32 v21, 0xffff0000, v45
	v_pk_fma_f32 v[10:11], v[12:13], v[20:21], v[10:11]
	v_lshlrev_b32_e32 v12, 16, v38
	v_cvt_pk_bf16_f32 v17, v10, v11
	v_lshlrev_b32_e32 v10, 16, v34
	v_and_b32_e32 v11, 0xffff0000, v34
	v_pk_mul_f32 v[10:11], v[174:175], v[10:11]
	v_and_b32_e32 v13, 0xffff0000, v38
	v_pk_fma_f32 v[6:7], v[6:7], v[12:13], v[10:11]
	v_lshlrev_b32_e32 v10, 16, v35
	v_and_b32_e32 v11, 0xffff0000, v35
	v_pk_mul_f32 v[10:11], v[174:175], v[10:11]
	v_lshlrev_b32_e32 v12, 16, v39
	v_and_b32_e32 v13, 0xffff0000, v39
	v_pk_fma_f32 v[8:9], v[8:9], v[12:13], v[10:11]
	v_cvt_pk_bf16_f32 v6, v6, v7
	v_cvt_pk_bf16_f32 v7, v8, v9
	v_lshlrev_b32_e32 v8, 16, v36
	v_and_b32_e32 v9, 0xffff0000, v36
	v_pk_mul_f32 v[8:9], v[174:175], v[8:9]
	v_lshlrev_b32_e32 v10, 16, v40
	v_and_b32_e32 v11, 0xffff0000, v40
	v_pk_fma_f32 v[2:3], v[2:3], v[10:11], v[8:9]
	v_ashrrev_i32_e32 v19, 31, v18
	v_cvt_pk_bf16_f32 v8, v2, v3
	v_lshlrev_b32_e32 v2, 16, v37
	v_and_b32_e32 v3, 0xffff0000, v37
	v_lshlrev_b64 v[18:19], 11, v[18:19]
	v_pk_mul_f32 v[2:3], v[174:175], v[2:3]
	v_lshlrev_b32_e32 v10, 16, v41
	v_and_b32_e32 v11, 0xffff0000, v41
	v_lshl_add_u64 v[18:19], s[0:1], 0, v[18:19]
	v_pk_fma_f32 v[2:3], v[4:5], v[10:11], v[2:3]
	v_lshl_add_u64 v[18:19], v[18:19], 0, v[172:173]
	v_cvt_pk_bf16_f32 v9, v2, v3
	s_and_b64 vcc, exec, s[36:37]
	s_mov_b32 s38, s68
	s_mov_b32 s2, s46
	s_mov_b64 s[90:91], s[88:89]
	s_mov_b64 s[62:63], s[84:85]
	global_store_dwordx4 v[66:67], v[30:33], off
	global_store_dwordx4 v[18:19], v[14:17], off
	global_store_dwordx4 v[18:19], v[6:9], off offset:64
	s_cbranch_vccnz .LBB0_545

.LBB0_533:
	v_cndmask_b32_e64 v174, 1.0, 0, s[62:63]
	s_cmpk_gt_u32 s9, 0xff
	s_cbranch_scc1 .Lepi0_branch0
	s_barrier
.Lepi0_branch0:
	s_waitcnt vmcnt(0)
	v_lshlrev_b32_e32 v204, 16, v158
	v_and_b32_e32 v205, 0xffff0000, v158
	v_lshlrev_b32_e32 v158, 16, v159
	v_and_b32_e32 v159, 0xffff0000, v159
	v_pk_mul_f32 v[204:205], v[174:175], v[204:205] op_sel_hi:[0,1]
	v_lshlrev_b32_e32 v206, 16, v154
	v_and_b32_e32 v207, 0xffff0000, v154
	v_pk_mul_f32 v[158:159], v[174:175], v[158:159] op_sel_hi:[0,1]
	v_lshlrev_b32_e32 v154, 16, v155
	v_and_b32_e32 v155, 0xffff0000, v155
	v_pk_fma_f32 v[126:127], v[126:127], v[206:207], v[204:205]
	v_pk_fma_f32 v[128:129], v[128:129], v[154:155], v[158:159]
	v_cvt_pk_bf16_f32 v126, v126, v127
	v_cvt_pk_bf16_f32 v127, v128, v129
	v_lshlrev_b32_e32 v128, 16, v160
	v_and_b32_e32 v129, 0xffff0000, v160
	v_pk_mul_f32 v[128:129], v[174:175], v[128:129] op_sel_hi:[0,1]
	v_lshlrev_b32_e32 v154, 16, v156
	v_and_b32_e32 v155, 0xffff0000, v156
	v_pk_fma_f32 v[122:123], v[122:123], v[154:155], v[128:129]
	v_lshlrev_b32_e32 v154, 16, v157
	v_cvt_pk_bf16_f32 v128, v122, v123
	v_lshlrev_b32_e32 v122, 16, v161
	v_and_b32_e32 v123, 0xffff0000, v161
	v_pk_mul_f32 v[122:123], v[174:175], v[122:123] op_sel_hi:[0,1]
	v_and_b32_e32 v155, 0xffff0000, v157
	v_pk_fma_f32 v[122:123], v[124:125], v[154:155], v[122:123]
	v_lshlrev_b32_e32 v124, 16, v138
	v_cvt_pk_bf16_f32 v129, v122, v123
	v_lshlrev_b32_e32 v122, 16, v146
	v_and_b32_e32 v123, 0xffff0000, v146
	v_pk_mul_f32 v[122:123], v[174:175], v[122:123] op_sel_hi:[0,1]
	v_and_b32_e32 v125, 0xffff0000, v138
	v_pk_fma_f32 v[118:119], v[118:119], v[124:125], v[122:123]
	v_lshlrev_b32_e32 v122, 16, v147
	v_and_b32_e32 v123, 0xffff0000, v147
	v_pk_mul_f32 v[122:123], v[174:175], v[122:123] op_sel_hi:[0,1]
	v_lshlrev_b32_e32 v124, 16, v139
	v_and_b32_e32 v125, 0xffff0000, v139
	v_pk_fma_f32 v[120:121], v[120:121], v[124:125], v[122:123]
	v_cvt_pk_bf16_f32 v118, v118, v119
	v_cvt_pk_bf16_f32 v119, v120, v121
	v_lshlrev_b32_e32 v120, 16, v148
	v_and_b32_e32 v121, 0xffff0000, v148
	v_pk_mul_f32 v[120:121], v[174:175], v[120:121] op_sel_hi:[0,1]
	v_lshlrev_b32_e32 v122, 16, v140
	v_and_b32_e32 v123, 0xffff0000, v140
	v_pk_fma_f32 v[114:115], v[114:115], v[122:123], v[120:121]
	v_lshlrev_b64 v[180:181], 11, v[170:171]
	v_cvt_pk_bf16_f32 v120, v114, v115
	v_lshlrev_b32_e32 v114, 16, v149
	v_and_b32_e32 v115, 0xffff0000, v149
	v_pk_mul_f32 v[114:115], v[174:175], v[114:115] op_sel_hi:[0,1]
	v_lshlrev_b32_e32 v122, 16, v141
	v_and_b32_e32 v123, 0xffff0000, v141
	v_lshl_add_u64 v[180:181], s[0:1], 0, v[180:181]
	v_mov_b32_e32 v173, v1
	v_pk_fma_f32 v[114:115], v[116:117], v[122:123], v[114:115]
	v_lshl_add_u64 v[180:181], v[180:181], 0, v[172:173]
	v_cvt_pk_bf16_f32 v121, v114, v115
	v_lshlrev_b32_e32 v116, 16, v150
	v_and_b32_e32 v117, 0xffff0000, v150
	global_store_dwordx4 v[180:181], v[118:121], off offset:64
	v_pk_mul_f32 v[116:117], v[174:175], v[116:117] op_sel_hi:[0,1]
	v_or_b32_e32 v114, 16, v170
	v_lshlrev_b32_e32 v118, 16, v142
	v_and_b32_e32 v119, 0xffff0000, v142
	v_pk_fma_f32 v[110:111], v[110:111], v[118:119], v[116:117]
	v_lshlrev_b32_e32 v116, 16, v151
	v_and_b32_e32 v117, 0xffff0000, v151
	v_pk_mul_f32 v[116:117], v[174:175], v[116:117] op_sel_hi:[0,1]
	v_lshlrev_b32_e32 v118, 16, v143
	v_and_b32_e32 v119, 0xffff0000, v143
	v_pk_fma_f32 v[112:113], v[112:113], v[118:119], v[116:117]
	v_cvt_pk_bf16_f32 v110, v110, v111
	v_cvt_pk_bf16_f32 v111, v112, v113
	v_lshlrev_b32_e32 v112, 16, v152
	v_and_b32_e32 v113, 0xffff0000, v152
	v_pk_mul_f32 v[112:113], v[174:175], v[112:113] op_sel_hi:[0,1]
	v_lshlrev_b32_e32 v116, 16, v144
	v_and_b32_e32 v117, 0xffff0000, v144
	v_pk_fma_f32 v[106:107], v[106:107], v[116:117], v[112:113]
	v_lshlrev_b32_e32 v116, 16, v145
	v_cvt_pk_bf16_f32 v112, v106, v107
	v_lshlrev_b32_e32 v106, 16, v153
	v_and_b32_e32 v107, 0xffff0000, v153
	v_pk_mul_f32 v[106:107], v[174:175], v[106:107] op_sel_hi:[0,1]
	v_and_b32_e32 v117, 0xffff0000, v145
	v_pk_fma_f32 v[106:107], v[108:109], v[116:117], v[106:107]
	v_lshlrev_b32_e32 v108, 16, v134
	v_cvt_pk_bf16_f32 v113, v106, v107
	v_lshlrev_b32_e32 v106, 16, v130
	v_and_b32_e32 v107, 0xffff0000, v130
	v_pk_mul_f32 v[106:107], v[174:175], v[106:107] op_sel_hi:[0,1]
	v_and_b32_e32 v109, 0xffff0000, v134
	v_pk_fma_f32 v[102:103], v[102:103], v[108:109], v[106:107]
	v_lshlrev_b32_e32 v106, 16, v131
	v_and_b32_e32 v107, 0xffff0000, v131
	v_pk_mul_f32 v[106:107], v[174:175], v[106:107] op_sel_hi:[0,1]
	v_lshlrev_b32_e32 v108, 16, v135
	v_and_b32_e32 v109, 0xffff0000, v135
	v_pk_fma_f32 v[104:105], v[104:105], v[108:109], v[106:107]
	v_cvt_pk_bf16_f32 v102, v102, v103
	v_cvt_pk_bf16_f32 v103, v104, v105
	v_lshlrev_b32_e32 v104, 16, v132
	v_and_b32_e32 v105, 0xffff0000, v132
	v_pk_mul_f32 v[104:105], v[174:175], v[104:105] op_sel_hi:[0,1]
	v_lshlrev_b32_e32 v106, 16, v136
	v_and_b32_e32 v107, 0xffff0000, v136
	v_pk_fma_f32 v[98:99], v[98:99], v[106:107], v[104:105]
	v_lshlrev_b32_e32 v106, 16, v137
	v_cvt_pk_bf16_f32 v104, v98, v99
	v_lshlrev_b32_e32 v98, 16, v133
	v_and_b32_e32 v99, 0xffff0000, v133
	v_pk_mul_f32 v[98:99], v[174:175], v[98:99] op_sel_hi:[0,1]
	v_and_b32_e32 v107, 0xffff0000, v137
	v_pk_fma_f32 v[98:99], v[100:101], v[106:107], v[98:99]
	v_add_u32_e32 v100, s2, v188
	v_lshrrev_b32_e32 v0, 8, v100
	v_ashrrev_i32_e32 v115, 31, v114
	v_cvt_pk_bf16_f32 v105, v98, v99
	v_mad_i32_i24 v98, v0, 38, v203
	v_lshlrev_b64 v[114:115], 11, v[114:115]
	v_ashrrev_i32_e32 v99, 31, v98
	v_lshl_add_u64 v[114:115], s[0:1], 0, v[114:115]
	v_or_b32_e32 v0, v202, v189
	v_lshlrev_b64 v[98:99], 17, v[98:99]
	v_lshl_add_u64 v[114:115], v[114:115], 0, v[172:173]
	v_lshl_add_u64 v[98:99], s[40:41], 0, v[98:99]
	v_lshlrev_b32_e32 v0, 1, v0
	global_store_dwordx4 v[180:181], v[126:129], off
	global_store_dwordx4 v[114:115], v[110:113], off
	global_store_dwordx4 v[114:115], v[102:105], off offset:64
	v_lshl_add_u64 v[98:99], v[98:99], 0, v[0:1]
	global_load_dwordx4 v[122:125], v[98:99], off
	global_load_dwordx4 v[110:113], v[98:99], off offset:64
	v_mov_b32_e32 v98, 0
	s_and_b64 vcc, exec, s[38:39]
	v_mov_b32_e32 v114, 0
	v_mov_b32_e32 v115, 0
	v_mov_b32_e32 v116, 0
	v_mov_b32_e32 v117, 0
	v_mov_b32_e32 v126, 0
	v_mov_b32_e32 v127, 0
	v_mov_b32_e32 v128, 0
	v_mov_b32_e32 v129, 0
	s_cbranch_vccnz .LBB0_535
	v_ashrrev_i32_e32 v101, 31, v100
	v_lshlrev_b64 v[100:101], 11, v[100:101]
	v_lshl_add_u64 v[100:101], v[176:177], 0, v[100:101]
	global_load_dwordx4 v[126:129], v[100:101], off
	global_load_dwordx4 v[114:117], v[100:101], off offset:64

.LBB0_618:
	ds_read_b128 v[48:51], v185
	ds_read_b128 v[52:55], v185 offset:1024
	ds_read_b128 v[56:59], v185 offset:2048
	ds_read_b128 v[60:63], v185 offset:3072
	s_add_u32 s47, s48, 0xfffc0080
	s_addc_u32 s50, s49, -1
	s_cmp_eq_u32 s35, 12
	s_cselect_b32 s55, s3, s50
	s_cselect_b32 s54, s21, s47
	s_cselect_b32 s53, s22, s33
	s_cselect_b32 s52, s23, s31
	v_lshl_add_u64 v[180:181], s[48:49], 0, v[164:165]
	s_add_i32 m0, s11, 0xc000
	ds_read_b128 v[144:147], v186
	ds_read_b128 v[148:151], v186 offset:1024
	ds_read_b128 v[152:155], v186 offset:2048
	ds_read_b128 v[156:159], v186 offset:3072
	ds_read_b128 v[172:175], v186 offset:4096
	ds_read_b128 v[176:179], v186 offset:5120
	ds_read_b128 v[188:191], v186 offset:6144
	ds_read_b128 v[192:195], v186 offset:7168
	global_load_lds_dwordx4 v[180:181], off
	v_lshl_add_u64 v[180:181], s[48:49], 0, v[166:167]
	s_add_i32 m0, s11, 0xe000
	s_nop 0
	global_load_lds_dwordx4 v[180:181], off
	s_waitcnt lgkmcnt(8)
	s_barrier
	s_waitcnt lgkmcnt(0)
	s_waitcnt lgkmcnt(0)
	v_mfma_f32_16x16x32_bf16 v[140:143], v[48:51], v[144:147], v[140:143]
	v_mfma_f32_16x16x32_bf16 v[136:139], v[56:59], v[144:147], v[136:139]
	v_mfma_f32_16x16x32_bf16 v[124:127], v[48:51], v[152:155], v[124:127]
	v_mfma_f32_16x16x32_bf16 v[120:123], v[56:59], v[152:155], v[120:123]
	v_mfma_f32_16x16x32_bf16 v[108:111], v[48:51], v[172:175], v[108:111]
	v_mfma_f32_16x16x32_bf16 v[104:107], v[56:59], v[172:175], v[104:107]
	v_mfma_f32_16x16x32_bf16 v[92:95], v[48:51], v[188:191], v[92:95]
	v_mfma_f32_16x16x32_bf16 v[88:91], v[56:59], v[188:191], v[88:91]
	v_mfma_f32_16x16x32_bf16 v[140:143], v[52:55], v[148:151], v[140:143]
	v_mfma_f32_16x16x32_bf16 v[136:139], v[60:63], v[148:151], v[136:139]
	v_mfma_f32_16x16x32_bf16 v[124:127], v[52:55], v[156:159], v[124:127]
	v_mfma_f32_16x16x32_bf16 v[120:123], v[60:63], v[156:159], v[120:123]
	v_mfma_f32_16x16x32_bf16 v[108:111], v[52:55], v[176:179], v[108:111]
	v_mfma_f32_16x16x32_bf16 v[104:107], v[60:63], v[176:179], v[104:107]
	v_mfma_f32_16x16x32_bf16 v[92:95], v[52:55], v[192:195], v[92:95]
	v_mfma_f32_16x16x32_bf16 v[88:91], v[60:63], v[192:195], v[88:91]
	s_barrier
	s_add_i32 s47, s19, s10
	v_lshl_add_u64 v[180:181], s[52:53], 0, v[160:161]
	s_mov_b32 m0, s47
	ds_read_b128 v[196:199], v187
	ds_read_b128 v[200:203], v187 offset:1024
	ds_read_b128 v[204:207], v187 offset:2048
	ds_read_b128 v[208:211], v187 offset:3072
	global_load_lds_dwordx4 v[180:181], off
	v_lshl_add_u64 v[212:213], s[52:53], 0, v[162:163]
	s_add_i32 m0, s47, 0x2000
	s_nop 0
	global_load_lds_dwordx4 v[212:213], off
	s_barrier
	s_waitcnt lgkmcnt(0)
	s_waitcnt lgkmcnt(0)
	v_mfma_f32_16x16x32_bf16 v[132:135], v[196:199], v[144:147], v[132:135]
	v_mfma_f32_16x16x32_bf16 v[128:131], v[204:207], v[144:147], v[128:131]
	v_mfma_f32_16x16x32_bf16 v[116:119], v[196:199], v[152:155], v[116:119]
	v_mfma_f32_16x16x32_bf16 v[112:115], v[204:207], v[152:155], v[112:115]
	v_mfma_f32_16x16x32_bf16 v[100:103], v[196:199], v[172:175], v[100:103]
	v_mfma_f32_16x16x32_bf16 v[96:99], v[204:207], v[172:175], v[96:99]
	v_mfma_f32_16x16x32_bf16 v[84:87], v[196:199], v[188:191], v[84:87]
	v_mfma_f32_16x16x32_bf16 v[80:83], v[204:207], v[188:191], v[80:83]
	v_mfma_f32_16x16x32_bf16 v[132:135], v[200:203], v[148:151], v[132:135]
	v_mfma_f32_16x16x32_bf16 v[128:131], v[208:211], v[148:151], v[128:131]
	v_mfma_f32_16x16x32_bf16 v[116:119], v[200:203], v[156:159], v[116:119]
	v_mfma_f32_16x16x32_bf16 v[112:115], v[208:211], v[156:159], v[112:115]
	v_mfma_f32_16x16x32_bf16 v[100:103], v[200:203], v[176:179], v[100:103]
	v_mfma_f32_16x16x32_bf16 v[96:99], v[208:211], v[176:179], v[96:99]
	v_mfma_f32_16x16x32_bf16 v[84:87], v[200:203], v[192:195], v[84:87]
	v_mfma_f32_16x16x32_bf16 v[80:83], v[208:211], v[192:195], v[80:83]
	s_mov_b32 m0, s11
	v_lshl_add_u64 v[214:215], s[54:55], 0, v[160:161]
	s_barrier
	ds_read_b128 v[144:147], v186 offset:16384
	ds_read_b128 v[148:151], v186 offset:17408
	ds_read_b128 v[152:155], v186 offset:18432
	ds_read_b128 v[156:159], v186 offset:19456
	ds_read_b128 v[172:175], v186 offset:20480
	ds_read_b128 v[176:179], v186 offset:21504
	ds_read_b128 v[188:191], v186 offset:22528
	ds_read_b128 v[192:195], v186 offset:23552
	global_load_lds_dwordx4 v[214:215], off
	v_lshl_add_u64 v[216:217], s[54:55], 0, v[162:163]
	s_mov_b32 m0, s12
	s_nop 0
	global_load_lds_dwordx4 v[216:217], off
	s_barrier
	s_waitcnt lgkmcnt(0)
	s_waitcnt lgkmcnt(0)
	v_mfma_f32_16x16x32_bf16 v[76:79], v[48:51], v[144:147], v[76:79]
	v_mfma_f32_16x16x32_bf16 v[72:75], v[56:59], v[144:147], v[72:75]
	v_mfma_f32_16x16x32_bf16 v[44:47], v[48:51], v[152:155], v[44:47]
	v_mfma_f32_16x16x32_bf16 v[40:43], v[56:59], v[152:155], v[40:43]
	v_mfma_f32_16x16x32_bf16 v[28:31], v[48:51], v[172:175], v[28:31]
	v_mfma_f32_16x16x32_bf16 v[24:27], v[56:59], v[172:175], v[24:27]
	v_mfma_f32_16x16x32_bf16 v[12:15], v[48:51], v[188:191], v[12:15]
	v_mfma_f32_16x16x32_bf16 v[8:11], v[56:59], v[188:191], v[8:11]
	v_mfma_f32_16x16x32_bf16 v[76:79], v[52:55], v[148:151], v[76:79]
	v_mfma_f32_16x16x32_bf16 v[72:75], v[60:63], v[148:151], v[72:75]
	v_mfma_f32_16x16x32_bf16 v[44:47], v[52:55], v[156:159], v[44:47]
	v_mfma_f32_16x16x32_bf16 v[40:43], v[60:63], v[156:159], v[40:43]
	v_mfma_f32_16x16x32_bf16 v[28:31], v[52:55], v[176:179], v[28:31]
	v_mfma_f32_16x16x32_bf16 v[24:27], v[60:63], v[176:179], v[24:27]
	v_mfma_f32_16x16x32_bf16 v[12:15], v[52:55], v[192:195], v[12:15]
	v_mfma_f32_16x16x32_bf16 v[8:11], v[60:63], v[192:195], v[8:11]
	s_barrier
	s_add_u32 s50, s52, 0x40000
	s_addc_u32 s51, s53, 0
	s_add_i32 s47, s20, s10
	v_lshl_add_u64 v[48:49], s[50:51], 0, v[160:161]
	s_mov_b32 m0, s47
	s_nop 0
	global_load_lds_dwordx4 v[48:49], off
	v_lshl_add_u64 v[48:49], s[50:51], 0, v[162:163]
	s_add_i32 m0, s47, 0x2000
	s_nop 0
	global_load_lds_dwordx4 v[48:49], off
	s_waitcnt vmcnt(6)
	s_barrier
	v_mfma_f32_16x16x32_bf16 v[36:39], v[196:199], v[152:155], v[36:39]
	v_mfma_f32_16x16x32_bf16 v[32:35], v[204:207], v[152:155], v[32:35]
	v_mfma_f32_16x16x32_bf16 v[20:23], v[196:199], v[172:175], v[20:23]
	v_mfma_f32_16x16x32_bf16 v[16:19], v[204:207], v[172:175], v[16:19]
	v_mfma_f32_16x16x32_bf16 v[4:7], v[196:199], v[188:191], v[4:7]
	v_mfma_f32_16x16x32_bf16 v[0:3], v[204:207], v[188:191], v[0:3]
	v_mfma_f32_16x16x32_bf16 v[48:51], v[196:199], v[144:147], v[68:71]
	v_mfma_f32_16x16x32_bf16 v[52:55], v[204:207], v[144:147], v[64:67]
	v_mfma_f32_16x16x32_bf16 v[36:39], v[200:203], v[156:159], v[36:39]
	v_mfma_f32_16x16x32_bf16 v[32:35], v[208:211], v[156:159], v[32:35]
	v_mfma_f32_16x16x32_bf16 v[20:23], v[200:203], v[176:179], v[20:23]
	v_mfma_f32_16x16x32_bf16 v[16:19], v[208:211], v[176:179], v[16:19]
	v_mfma_f32_16x16x32_bf16 v[4:7], v[200:203], v[192:195], v[4:7]
	v_mfma_f32_16x16x32_bf16 v[0:3], v[208:211], v[192:195], v[0:3]
	v_mfma_f32_16x16x32_bf16 v[48:51], v[200:203], v[148:151], v[48:51]
	v_mfma_f32_16x16x32_bf16 v[52:55], v[208:211], v[148:151], v[52:55]
	s_add_i32 s47, 0, 0x18000
	v_add_u32_e32 v68, s47, v183
	s_barrier
	ds_read_b128 v[56:59], v68
	ds_read_b128 v[60:63], v68 offset:1024
	ds_read_b128 v[64:67], v68 offset:2048
	ds_read_b128 v[68:71], v68 offset:3072
	s_add_u32 s50, s54, 0x40000
	s_addc_u32 s51, s55, 0
	s_mov_b32 m0, s13
	v_lshl_add_u64 v[196:197], s[50:51], 0, v[160:161]
	ds_read_b128 v[144:147], v186 offset:32768
	ds_read_b128 v[148:151], v186 offset:33792
	ds_read_b128 v[152:155], v186 offset:34816
	ds_read_b128 v[156:159], v186 offset:35840
	ds_read_b128 v[172:175], v186 offset:36864
	ds_read_b128 v[176:179], v186 offset:37888
	ds_read_b128 v[188:191], v186 offset:38912
	ds_read_b128 v[192:195], v186 offset:39936
	global_load_lds_dwordx4 v[196:197], off
	v_lshl_add_u64 v[196:197], s[50:51], 0, v[162:163]
	s_mov_b32 m0, s14
	s_nop 0
	global_load_lds_dwordx4 v[196:197], off
	s_waitcnt lgkmcnt(8)
	s_barrier
	s_waitcnt lgkmcnt(0)
	s_waitcnt lgkmcnt(0)
	v_mfma_f32_16x16x32_bf16 v[140:143], v[56:59], v[144:147], v[140:143]
	v_mfma_f32_16x16x32_bf16 v[136:139], v[64:67], v[144:147], v[136:139]
	v_mfma_f32_16x16x32_bf16 v[124:127], v[56:59], v[152:155], v[124:127]
	v_mfma_f32_16x16x32_bf16 v[120:123], v[64:67], v[152:155], v[120:123]
	v_mfma_f32_16x16x32_bf16 v[108:111], v[56:59], v[172:175], v[108:111]
	v_mfma_f32_16x16x32_bf16 v[104:107], v[64:67], v[172:175], v[104:107]
	v_mfma_f32_16x16x32_bf16 v[92:95], v[56:59], v[188:191], v[92:95]
	v_mfma_f32_16x16x32_bf16 v[88:91], v[64:67], v[188:191], v[88:91]
	v_mfma_f32_16x16x32_bf16 v[140:143], v[60:63], v[148:151], v[140:143]
	v_mfma_f32_16x16x32_bf16 v[136:139], v[68:71], v[148:151], v[136:139]
	v_mfma_f32_16x16x32_bf16 v[124:127], v[60:63], v[156:159], v[124:127]
	v_mfma_f32_16x16x32_bf16 v[120:123], v[68:71], v[156:159], v[120:123]
	v_mfma_f32_16x16x32_bf16 v[108:111], v[60:63], v[176:179], v[108:111]
	v_mfma_f32_16x16x32_bf16 v[104:107], v[68:71], v[176:179], v[104:107]
	v_mfma_f32_16x16x32_bf16 v[92:95], v[60:63], v[192:195], v[92:95]
	v_mfma_f32_16x16x32_bf16 v[88:91], v[68:71], v[192:195], v[88:91]
	s_barrier
	s_add_i32 s54, 0, 0x1c000
	s_add_i32 s47, s47, s10
	v_add_u32_e32 v208, s54, v183
	v_lshl_add_u64 v[180:181], v[180:181], 0, s[28:29]
	s_mov_b32 m0, s47
	ds_read_b128 v[196:199], v208
	ds_read_b128 v[200:203], v208 offset:1024
	ds_read_b128 v[204:207], v208 offset:2048
	ds_read_b128 v[208:211], v208 offset:3072
	global_load_lds_dwordx4 v[180:181], off
	v_lshl_add_u64 v[180:181], v[212:213], 0, s[28:29]
	s_add_i32 m0, s47, 0x2000
	s_nop 0
	global_load_lds_dwordx4 v[180:181], off
	s_barrier
	s_waitcnt lgkmcnt(0)
	s_waitcnt lgkmcnt(0)
	v_mfma_f32_16x16x32_bf16 v[132:135], v[196:199], v[144:147], v[132:135]
	v_mfma_f32_16x16x32_bf16 v[128:131], v[204:207], v[144:147], v[128:131]
	v_mfma_f32_16x16x32_bf16 v[116:119], v[196:199], v[152:155], v[116:119]
	v_mfma_f32_16x16x32_bf16 v[112:115], v[204:207], v[152:155], v[112:115]
	v_mfma_f32_16x16x32_bf16 v[100:103], v[196:199], v[172:175], v[100:103]
	v_mfma_f32_16x16x32_bf16 v[96:99], v[204:207], v[172:175], v[96:99]
	v_mfma_f32_16x16x32_bf16 v[84:87], v[196:199], v[188:191], v[84:87]
	v_mfma_f32_16x16x32_bf16 v[80:83], v[204:207], v[188:191], v[80:83]
	v_mfma_f32_16x16x32_bf16 v[132:135], v[200:203], v[148:151], v[132:135]
	v_mfma_f32_16x16x32_bf16 v[128:131], v[208:211], v[148:151], v[128:131]
	v_mfma_f32_16x16x32_bf16 v[116:119], v[200:203], v[156:159], v[116:119]
	v_mfma_f32_16x16x32_bf16 v[112:115], v[208:211], v[156:159], v[112:115]
	v_mfma_f32_16x16x32_bf16 v[100:103], v[200:203], v[176:179], v[100:103]
	v_mfma_f32_16x16x32_bf16 v[96:99], v[208:211], v[176:179], v[96:99]
	v_mfma_f32_16x16x32_bf16 v[84:87], v[200:203], v[192:195], v[84:87]
	v_mfma_f32_16x16x32_bf16 v[80:83], v[208:211], v[192:195], v[80:83]
	s_mov_b32 m0, s16
	v_lshl_add_u64 v[180:181], v[214:215], 0, s[28:29]
	s_barrier
	ds_read_b128 v[144:147], v186 offset:49152
	ds_read_b128 v[148:151], v186 offset:50176
	ds_read_b128 v[152:155], v186 offset:51200
	ds_read_b128 v[156:159], v186 offset:52224
	ds_read_b128 v[172:175], v186 offset:53248
	ds_read_b128 v[176:179], v186 offset:54272
	ds_read_b128 v[188:191], v186 offset:55296
	ds_read_b128 v[192:195], v186 offset:56320
	global_load_lds_dwordx4 v[180:181], off
	v_lshl_add_u64 v[180:181], v[216:217], 0, s[28:29]
	s_mov_b32 m0, s17
	s_nop 0
	global_load_lds_dwordx4 v[180:181], off
	s_barrier
	s_waitcnt lgkmcnt(0)
	s_waitcnt lgkmcnt(0)
	v_mfma_f32_16x16x32_bf16 v[76:79], v[56:59], v[144:147], v[76:79]
	v_mfma_f32_16x16x32_bf16 v[72:75], v[64:67], v[144:147], v[72:75]
	v_mfma_f32_16x16x32_bf16 v[44:47], v[56:59], v[152:155], v[44:47]
	v_mfma_f32_16x16x32_bf16 v[40:43], v[64:67], v[152:155], v[40:43]
	v_mfma_f32_16x16x32_bf16 v[28:31], v[56:59], v[172:175], v[28:31]
	v_mfma_f32_16x16x32_bf16 v[24:27], v[64:67], v[172:175], v[24:27]
	v_mfma_f32_16x16x32_bf16 v[12:15], v[56:59], v[188:191], v[12:15]
	v_mfma_f32_16x16x32_bf16 v[8:11], v[64:67], v[188:191], v[8:11]
	v_mfma_f32_16x16x32_bf16 v[76:79], v[60:63], v[148:151], v[76:79]
	v_mfma_f32_16x16x32_bf16 v[72:75], v[68:71], v[148:151], v[72:75]
	v_mfma_f32_16x16x32_bf16 v[44:47], v[60:63], v[156:159], v[44:47]
	v_mfma_f32_16x16x32_bf16 v[40:43], v[68:71], v[156:159], v[40:43]
	v_mfma_f32_16x16x32_bf16 v[28:31], v[60:63], v[176:179], v[28:31]
	v_mfma_f32_16x16x32_bf16 v[24:27], v[68:71], v[176:179], v[24:27]
	v_mfma_f32_16x16x32_bf16 v[12:15], v[60:63], v[192:195], v[12:15]
	v_mfma_f32_16x16x32_bf16 v[8:11], v[68:71], v[192:195], v[8:11]
	s_barrier
	s_add_u32 s50, s52, 0x40080
	s_addc_u32 s51, s53, 0
	s_add_i32 s47, s54, s10
	v_lshl_add_u64 v[56:57], s[50:51], 0, v[160:161]
	s_mov_b32 m0, s47
	s_nop 0
	global_load_lds_dwordx4 v[56:57], off
	v_lshl_add_u64 v[56:57], s[50:51], 0, v[162:163]
	s_add_i32 m0, s47, 0x2000
	s_nop 0
	global_load_lds_dwordx4 v[56:57], off
	s_waitcnt vmcnt(6)
	s_barrier
	v_mfma_f32_16x16x32_bf16 v[48:51], v[196:199], v[144:147], v[48:51]
	v_mfma_f32_16x16x32_bf16 v[68:71], v[200:203], v[148:151], v[48:51]
	v_mfma_f32_16x16x32_bf16 v[48:51], v[204:207], v[144:147], v[52:55]
	v_mfma_f32_16x16x32_bf16 v[36:39], v[196:199], v[152:155], v[36:39]
	v_mfma_f32_16x16x32_bf16 v[32:35], v[204:207], v[152:155], v[32:35]
	v_mfma_f32_16x16x32_bf16 v[20:23], v[196:199], v[172:175], v[20:23]
	v_mfma_f32_16x16x32_bf16 v[16:19], v[204:207], v[172:175], v[16:19]
	v_mfma_f32_16x16x32_bf16 v[4:7], v[196:199], v[188:191], v[4:7]
	v_mfma_f32_16x16x32_bf16 v[0:3], v[204:207], v[188:191], v[0:3]
	v_mfma_f32_16x16x32_bf16 v[64:67], v[208:211], v[148:151], v[48:51]
	v_mfma_f32_16x16x32_bf16 v[36:39], v[200:203], v[156:159], v[36:39]
	v_mfma_f32_16x16x32_bf16 v[32:35], v[208:211], v[156:159], v[32:35]
	v_mfma_f32_16x16x32_bf16 v[20:23], v[200:203], v[176:179], v[20:23]
	v_mfma_f32_16x16x32_bf16 v[16:19], v[208:211], v[176:179], v[16:19]
	v_mfma_f32_16x16x32_bf16 v[4:7], v[200:203], v[192:195], v[4:7]
	v_mfma_f32_16x16x32_bf16 v[0:3], v[208:211], v[192:195], v[0:3]
	s_add_i32 s35, s35, 2
	s_add_u32 s48, s48, 0x100
	s_addc_u32 s49, s49, 0
	s_add_u32 s31, s31, 0x100
	s_addc_u32 s33, s33, 0
	s_cmp_gt_u32 s35, 13
	s_barrier
	s_cbranch_scc0 .LBB0_618
	v_and_b32_e32 v145, 64, v229
	v_xor_b32_e32 v144, 16, v229
	v_add_u32_e32 v145, 64, v145
	v_cmp_lt_i32_e32 vcc, v144, v145
	v_lshl_or_b32 v172, s46, 8, v184
	v_ashrrev_i32_e32 v173, 31, v172
	v_cndmask_b32_e32 v144, v229, v144, vcc
	v_lshl_add_u32 v174, s2, 8, v182
	v_lshlrev_b32_e32 v189, 2, v144
	v_xor_b32_e32 v144, 32, v229
	v_lshlrev_b64 v[206:207], 2, v[172:173]
	v_cmp_lt_i32_e32 vcc, v144, v145
	v_ashrrev_i32_e32 v175, 31, v174
	v_lshl_add_u64 v[176:177], s[44:45], 0, v[206:207]
	v_cndmask_b32_e32 v144, v229, v144, vcc
	v_lshlrev_b64 v[208:209], 12, v[174:175]
	v_lshl_add_u64 v[56:57], s[56:57], 0, v[206:207]
	v_lshlrev_b32_e32 v188, 2, v144
	v_lshl_add_u64 v[144:145], v[176:177], 0, v[208:209]
	global_load_dwordx4 v[52:55], v[56:57], off offset:16
	global_load_dwordx4 v[60:63], v[56:57], off
	global_load_dwordx4 v[48:51], v[56:57], off offset:144
	s_nop 0
	global_load_dwordx4 v[56:59], v[56:57], off offset:128
	s_nop 0
	global_load_dwordx4 v[190:193], v[144:145], off offset:16
	global_load_dwordx4 v[194:197], v[144:145], off
	global_load_dwordx4 v[198:201], v[144:145], off offset:144
	global_load_dwordx4 v[202:205], v[144:145], off offset:128
	v_or_b32_e32 v178, 16, v174
	v_ashrrev_i32_e32 v179, 31, v178
	v_lshlrev_b64 v[180:181], 12, v[178:179]
	v_lshl_add_u64 v[148:149], v[176:177], 0, v[180:181]
	global_load_dwordx4 v[152:155], v[148:149], off offset:16
	global_load_dwordx4 v[156:159], v[148:149], off
	global_load_dwordx4 v[144:147], v[148:149], off offset:144
	s_nop 0
	global_load_dwordx4 v[148:151], v[148:149], off offset:128
	s_cmpk_gt_u32 s5, 0xff
	s_cbranch_scc1 .Lepi0_out0
	s_barrier
.Lepi0_out0:
	s_waitcnt vmcnt(0)
	v_pk_add_f32 v[136:137], v[136:137], v[190:191]
	v_pk_add_f32 v[194:195], v[140:141], v[194:195]
	v_pk_add_f32 v[198:199], v[128:129], v[198:199]
	v_lshl_add_u64 v[128:129], s[78:79], 0, v[208:209]
	v_pk_add_f32 v[196:197], v[142:143], v[196:197]
	v_pk_mul_f32 v[212:213], v[194:195], v[194:195]
	v_pk_add_f32 v[190:191], v[132:133], v[202:203]
	v_lshl_add_u64 v[128:129], v[128:129], 0, v[206:207]
	v_pk_mul_f32 v[210:211], v[196:197], v[196:197]
	v_pk_add_f32 v[138:139], v[138:139], v[192:193]
	v_pk_add_f32 v[192:193], v[134:135], v[204:205]
	v_pk_mul_f32 v[204:205], v[190:191], v[190:191]
	v_pk_add_f32 v[200:201], v[130:131], v[200:201]
	global_store_dwordx4 v[128:129], v[194:197], off nt
	global_store_dwordx4 v[128:129], v[136:139], off offset:16 nt
	global_store_dwordx4 v[128:129], v[190:193], off offset:128 nt
	global_store_dwordx4 v[128:129], v[198:201], off offset:144 nt
	v_pk_mul_f32 v[134:135], v[56:57], v[190:191]
	v_add_f32_e32 v190, v212, v213
	v_add_f32_e32 v190, v210, v190
	v_pk_mul_f32 v[216:217], v[136:137], v[136:137]
	v_add_f32_e32 v190, v211, v190
	v_add_f32_e32 v190, v216, v190
	v_pk_mul_f32 v[214:215], v[138:139], v[138:139]
	v_add_f32_e32 v190, v217, v190
	v_add_f32_e32 v190, v214, v190
	v_add_f32_e32 v190, v215, v190
	v_add_f32_e32 v190, v204, v190
	v_pk_mul_f32 v[202:203], v[192:193], v[192:193]
	v_add_f32_e32 v190, v205, v190
	v_add_f32_e32 v190, v202, v190
	v_pk_mul_f32 v[220:221], v[198:199], v[198:199]
	v_add_f32_e32 v190, v203, v190
	v_add_f32_e32 v190, v220, v190
	v_pk_mul_f32 v[218:219], v[200:201], v[200:201]
	v_add_f32_e32 v190, v221, v190
	v_add_f32_e32 v190, v218, v190
	v_pk_mul_f32 v[128:129], v[62:63], v[196:197]
	v_add_f32_e32 v196, v219, v190
	v_lshlrev_b64 v[190:191], 11, v[174:175]
	v_pk_mul_f32 v[142:143], v[60:61], v[194:195]
	v_pk_mul_f32 v[130:131], v[52:53], v[136:137]
	v_pk_mul_f32 v[132:133], v[54:55], v[138:139]
	v_lshl_add_u64 v[190:191], s[24:25], 0, v[190:191]
	v_pk_mul_f32 v[136:137], v[58:59], v[192:193]
	v_pk_mul_f32 v[138:139], v[48:49], v[198:199]
	v_pk_mul_f32 v[140:141], v[50:51], v[200:201]
	v_lshl_add_u64 v[194:195], v[172:173], 1, v[190:191]
	v_cvt_pk_bf16_f32 v190, v142, v143
	v_cvt_pk_bf16_f32 v191, v128, v129
	v_cvt_pk_bf16_f32 v192, v130, v131
	v_cvt_pk_bf16_f32 v193, v132, v133
	v_cvt_pk_bf16_f32 v128, v134, v135
	v_cvt_pk_bf16_f32 v129, v136, v137
	v_cvt_pk_bf16_f32 v130, v138, v139
	v_cvt_pk_bf16_f32 v131, v140, v141
	global_store_dwordx4 v[194:195], v[190:193], off nt
	global_store_dwordx4 v[194:195], v[128:131], off offset:64 nt
	ds_bpermute_b32 v128, v189, v196
	s_waitcnt lgkmcnt(0)
	v_add_f32_e32 v128, v196, v128
	ds_bpermute_b32 v129, v188, v128
	s_and_saveexec_b64 s[2:3], s[36:37]
	s_cbranch_execz .LBB0_621
	v_lshl_add_u64 v[130:131], v[174:175], 2, s[26:27]
	s_waitcnt lgkmcnt(0)
	v_add_f32_e32 v128, v128, v129
	global_atomic_add_f32 v[130:131], v128, off

.LBB0_703:
	ds_read_b128 v[44:47], v236
	ds_read_b128 v[48:51], v236 offset:1024
	ds_read_b128 v[52:55], v236 offset:2048
	ds_read_b128 v[56:59], v236 offset:3072
	s_add_u32 s0, vcc_lo, 0xfffc0080
	s_addc_u32 s1, vcc_hi, -1
	s_cmp_eq_u32 s59, 12
	s_cselect_b32 s91, s22, s1
	s_cselect_b32 s90, s23, s0
	s_cselect_b32 s1, s3, s57
	s_cselect_b32 s0, s51, s55
	v_lshl_add_u64 v[190:191], vcc, 0, v[166:167]
	s_add_i32 m0, s12, 0xc000
	ds_read_b128 v[68:71], v237
	ds_read_b128 v[72:75], v237 offset:1024
	ds_read_b128 v[76:79], v237 offset:2048
	ds_read_b128 v[80:83], v237 offset:3072
	ds_read_b128 v[174:177], v237 offset:4096
	ds_read_b128 v[178:181], v237 offset:5120
	ds_read_b128 v[182:185], v237 offset:6144
	ds_read_b128 v[186:189], v237 offset:7168
	global_load_lds_dwordx4 v[190:191], off
	v_lshl_add_u64 v[190:191], vcc, 0, v[168:169]
	s_add_i32 m0, s12, 0xe000
	s_nop 0
	global_load_lds_dwordx4 v[190:191], off
	s_waitcnt lgkmcnt(8)
	s_barrier
	s_waitcnt lgkmcnt(0)
	s_waitcnt lgkmcnt(0)
	v_mfma_f32_16x16x32_bf16 v[156:159], v[44:47], v[68:71], v[156:159]
	v_mfma_f32_16x16x32_bf16 v[132:135], v[52:55], v[68:71], v[132:135]
	v_mfma_f32_16x16x32_bf16 v[152:155], v[44:47], v[76:79], v[152:155]
	v_mfma_f32_16x16x32_bf16 v[128:131], v[52:55], v[76:79], v[128:131]
	v_mfma_f32_16x16x32_bf16 v[140:143], v[44:47], v[174:177], v[140:143]
	v_mfma_f32_16x16x32_bf16 v[104:107], v[52:55], v[174:177], v[104:107]
	v_mfma_f32_16x16x32_bf16 v[144:147], v[44:47], v[182:185], v[144:147]
	v_mfma_f32_16x16x32_bf16 v[108:111], v[52:55], v[182:185], v[108:111]
	v_mfma_f32_16x16x32_bf16 v[156:159], v[48:51], v[72:75], v[156:159]
	v_mfma_f32_16x16x32_bf16 v[132:135], v[56:59], v[72:75], v[132:135]
	v_mfma_f32_16x16x32_bf16 v[152:155], v[48:51], v[80:83], v[152:155]
	v_mfma_f32_16x16x32_bf16 v[128:131], v[56:59], v[80:83], v[128:131]
	v_mfma_f32_16x16x32_bf16 v[140:143], v[48:51], v[178:181], v[140:143]
	v_mfma_f32_16x16x32_bf16 v[104:107], v[56:59], v[178:181], v[104:107]
	v_mfma_f32_16x16x32_bf16 v[144:147], v[48:51], v[186:189], v[144:147]
	v_mfma_f32_16x16x32_bf16 v[108:111], v[56:59], v[186:189], v[108:111]
	s_barrier
	s_add_i32 s60, s20, s11
	v_lshl_add_u64 v[214:215], s[0:1], 0, v[160:161]
	s_mov_b32 m0, s60
	ds_read_b128 v[190:193], v238
	ds_read_b128 v[194:197], v238 offset:1024
	ds_read_b128 v[198:201], v238 offset:2048
	ds_read_b128 v[202:205], v238 offset:3072
	global_load_lds_dwordx4 v[214:215], off
	v_lshl_add_u64 v[216:217], s[0:1], 0, v[162:163]
	s_add_i32 m0, s60, 0x2000
	s_nop 0
	global_load_lds_dwordx4 v[216:217], off
	s_barrier
	s_waitcnt lgkmcnt(0)
	s_waitcnt lgkmcnt(0)
	v_mfma_f32_16x16x32_bf16 v[148:151], v[190:193], v[68:71], v[148:151]
	v_mfma_f32_16x16x32_bf16 v[68:71], v[198:201], v[68:71], v[124:127]
	v_mfma_f32_16x16x32_bf16 v[148:151], v[194:197], v[72:75], v[148:151]
	v_mfma_f32_16x16x32_bf16 v[68:71], v[202:205], v[72:75], v[68:71]
	v_mfma_f32_16x16x32_bf16 v[72:75], v[190:193], v[76:79], v[120:123]
	v_mfma_f32_16x16x32_bf16 v[76:79], v[198:201], v[76:79], v[112:115]
	v_mfma_f32_16x16x32_bf16 v[100:103], v[198:201], v[174:177], v[100:103]
	v_mfma_f32_16x16x32_bf16 v[112:115], v[190:193], v[182:185], v[136:139]
	v_mfma_f32_16x16x32_bf16 v[96:99], v[198:201], v[182:185], v[96:99]
	v_mfma_f32_16x16x32_bf16 v[72:75], v[194:197], v[80:83], v[72:75]
	v_mfma_f32_16x16x32_bf16 v[76:79], v[202:205], v[80:83], v[76:79]
	v_mfma_f32_16x16x32_bf16 v[80:83], v[190:193], v[174:177], v[116:119]
	v_mfma_f32_16x16x32_bf16 v[100:103], v[202:205], v[178:181], v[100:103]
	v_mfma_f32_16x16x32_bf16 v[136:139], v[194:197], v[186:189], v[112:115]
	v_mfma_f32_16x16x32_bf16 v[96:99], v[202:205], v[186:189], v[96:99]
	v_mfma_f32_16x16x32_bf16 v[80:83], v[194:197], v[178:181], v[80:83]
	s_mov_b32 m0, s12
	v_lshl_add_u64 v[218:219], s[90:91], 0, v[160:161]
	s_barrier
	ds_read_b128 v[112:115], v237 offset:16384
	ds_read_b128 v[116:119], v237 offset:17408
	ds_read_b128 v[120:123], v237 offset:18432
	ds_read_b128 v[124:127], v237 offset:19456
	ds_read_b128 v[174:177], v237 offset:20480
	ds_read_b128 v[178:181], v237 offset:21504
	ds_read_b128 v[182:185], v237 offset:22528
	ds_read_b128 v[186:189], v237 offset:23552
	global_load_lds_dwordx4 v[218:219], off
	v_lshl_add_u64 v[220:221], s[90:91], 0, v[162:163]
	s_mov_b32 m0, s13
	s_nop 0
	global_load_lds_dwordx4 v[220:221], off
	s_barrier
	s_waitcnt lgkmcnt(0)
	s_waitcnt lgkmcnt(0)
	v_mfma_f32_16x16x32_bf16 v[92:95], v[44:47], v[112:115], v[92:95]
	v_mfma_f32_16x16x32_bf16 v[40:43], v[52:55], v[112:115], v[40:43]
	v_mfma_f32_16x16x32_bf16 v[88:91], v[44:47], v[120:123], v[88:91]
	v_mfma_f32_16x16x32_bf16 v[36:39], v[52:55], v[120:123], v[36:39]
	v_mfma_f32_16x16x32_bf16 v[60:63], v[44:47], v[174:177], v[60:63]
	v_mfma_f32_16x16x32_bf16 v[8:11], v[52:55], v[174:177], v[8:11]
	v_mfma_f32_16x16x32_bf16 v[16:19], v[52:55], v[182:185], v[16:19]
	v_mfma_f32_16x16x32_bf16 v[92:95], v[48:51], v[116:119], v[92:95]
	v_mfma_f32_16x16x32_bf16 v[40:43], v[56:59], v[116:119], v[40:43]
	v_mfma_f32_16x16x32_bf16 v[88:91], v[48:51], v[124:127], v[88:91]
	v_mfma_f32_16x16x32_bf16 v[36:39], v[56:59], v[124:127], v[36:39]
	v_mfma_f32_16x16x32_bf16 v[60:63], v[48:51], v[178:181], v[60:63]
	v_mfma_f32_16x16x32_bf16 v[8:11], v[56:59], v[178:181], v[8:11]
	v_mfma_f32_16x16x32_bf16 v[44:47], v[44:47], v[182:185], v[64:67]
	v_mfma_f32_16x16x32_bf16 v[16:19], v[56:59], v[186:189], v[16:19]
	v_mfma_f32_16x16x32_bf16 v[44:47], v[48:51], v[186:189], v[44:47]
	s_barrier
	s_add_u32 s60, s0, 0x40000
	s_addc_u32 s61, s1, 0
	s_add_i32 s63, s21, s11
	v_lshl_add_u64 v[48:49], s[60:61], 0, v[160:161]
	s_mov_b32 m0, s63
	s_nop 0
	global_load_lds_dwordx4 v[48:49], off
	v_lshl_add_u64 v[48:49], s[60:61], 0, v[162:163]
	s_add_i32 m0, s63, 0x2000
	s_nop 0
	global_load_lds_dwordx4 v[48:49], off
	s_waitcnt vmcnt(6)
	s_barrier
	v_mfma_f32_16x16x32_bf16 v[28:31], v[198:201], v[112:115], v[28:31]
	v_mfma_f32_16x16x32_bf16 v[24:27], v[190:193], v[120:123], v[24:27]
	v_mfma_f32_16x16x32_bf16 v[12:15], v[198:201], v[120:123], v[12:15]
	v_mfma_f32_16x16x32_bf16 v[20:23], v[190:193], v[174:177], v[20:23]
	v_mfma_f32_16x16x32_bf16 v[4:7], v[198:201], v[174:177], v[4:7]
	v_mfma_f32_16x16x32_bf16 v[32:35], v[190:193], v[182:185], v[32:35]
	v_mfma_f32_16x16x32_bf16 v[0:3], v[198:201], v[182:185], v[0:3]
	v_mfma_f32_16x16x32_bf16 v[48:51], v[190:193], v[112:115], v[84:87]
	v_mfma_f32_16x16x32_bf16 v[28:31], v[202:205], v[116:119], v[28:31]
	v_mfma_f32_16x16x32_bf16 v[24:27], v[194:197], v[124:127], v[24:27]
	v_mfma_f32_16x16x32_bf16 v[12:15], v[202:205], v[124:127], v[12:15]
	v_mfma_f32_16x16x32_bf16 v[20:23], v[194:197], v[178:181], v[20:23]
	v_mfma_f32_16x16x32_bf16 v[4:7], v[202:205], v[178:181], v[4:7]
	v_mfma_f32_16x16x32_bf16 v[32:35], v[194:197], v[186:189], v[32:35]
	v_mfma_f32_16x16x32_bf16 v[0:3], v[202:205], v[186:189], v[0:3]
	v_mfma_f32_16x16x32_bf16 v[48:51], v[194:197], v[116:119], v[48:51]
	s_add_i32 s63, 0, 0x18000
	v_add_u32_e32 v64, s63, v232
	s_barrier
	ds_read_b128 v[52:55], v64
	ds_read_b128 v[56:59], v64 offset:1024
	ds_read_b128 v[84:87], v64 offset:2048
	ds_read_b128 v[174:177], v64 offset:3072
	s_add_u32 s60, s90, 0x40000
	s_addc_u32 s61, s91, 0
	s_mov_b32 m0, s14
	v_lshl_add_u64 v[120:121], s[60:61], 0, v[160:161]
	ds_read_b128 v[64:67], v237 offset:32768
	ds_read_b128 v[112:115], v237 offset:33792
	ds_read_b128 v[116:119], v237 offset:34816
	ds_read_b128 v[178:181], v237 offset:35840
	ds_read_b128 v[182:185], v237 offset:36864
	ds_read_b128 v[186:189], v237 offset:37888
	ds_read_b128 v[190:193], v237 offset:38912
	ds_read_b128 v[194:197], v237 offset:39936
	global_load_lds_dwordx4 v[120:121], off
	v_lshl_add_u64 v[120:121], s[60:61], 0, v[162:163]
	s_mov_b32 m0, s15
	s_nop 0
	global_load_lds_dwordx4 v[120:121], off
	s_waitcnt lgkmcnt(8)
	s_barrier
	s_waitcnt lgkmcnt(0)
	s_waitcnt lgkmcnt(0)
	v_mfma_f32_16x16x32_bf16 v[120:123], v[52:55], v[64:67], v[156:159]
	v_mfma_f32_16x16x32_bf16 v[156:159], v[56:59], v[112:115], v[120:123]
	v_mfma_f32_16x16x32_bf16 v[120:123], v[84:87], v[64:67], v[132:135]
	v_mfma_f32_16x16x32_bf16 v[132:135], v[174:177], v[112:115], v[120:123]
	v_mfma_f32_16x16x32_bf16 v[120:123], v[52:55], v[116:119], v[152:155]
	v_mfma_f32_16x16x32_bf16 v[152:155], v[56:59], v[178:181], v[120:123]
	v_mfma_f32_16x16x32_bf16 v[120:123], v[84:87], v[116:119], v[128:131]
	v_mfma_f32_16x16x32_bf16 v[128:131], v[174:177], v[178:181], v[120:123]
	v_mfma_f32_16x16x32_bf16 v[120:123], v[52:55], v[182:185], v[140:143]
	v_mfma_f32_16x16x32_bf16 v[140:143], v[56:59], v[186:189], v[120:123]
	v_mfma_f32_16x16x32_bf16 v[104:107], v[84:87], v[182:185], v[104:107]
	v_mfma_f32_16x16x32_bf16 v[120:123], v[52:55], v[190:193], v[144:147]
	v_mfma_f32_16x16x32_bf16 v[108:111], v[84:87], v[190:193], v[108:111]
	v_mfma_f32_16x16x32_bf16 v[104:107], v[174:177], v[186:189], v[104:107]
	v_mfma_f32_16x16x32_bf16 v[144:147], v[56:59], v[194:197], v[120:123]
	v_mfma_f32_16x16x32_bf16 v[108:111], v[174:177], v[194:197], v[108:111]
	s_barrier
	s_add_i32 s60, 0, 0x1c000
	s_nop 0
	v_add_u32_e32 v120, s60, v232
	s_add_i32 s61, s63, s11
	ds_read_b128 v[198:201], v120
	ds_read_b128 v[202:205], v120 offset:1024
	ds_read_b128 v[206:209], v120 offset:2048
	ds_read_b128 v[210:213], v120 offset:3072
	v_lshl_add_u64 v[120:121], v[214:215], 0, s[52:53]
	s_mov_b32 m0, s61
	s_nop 0
	global_load_lds_dwordx4 v[120:121], off
	v_lshl_add_u64 v[120:121], v[216:217], 0, s[52:53]
	s_add_i32 m0, s61, 0x2000
	s_nop 0
	global_load_lds_dwordx4 v[120:121], off
	s_barrier
	s_waitcnt lgkmcnt(0)
	s_waitcnt lgkmcnt(0)
	v_mfma_f32_16x16x32_bf16 v[120:123], v[198:201], v[64:67], v[148:151]
	v_mfma_f32_16x16x32_bf16 v[64:67], v[206:209], v[64:67], v[68:71]
	v_mfma_f32_16x16x32_bf16 v[124:127], v[210:213], v[112:115], v[64:67]
	v_mfma_f32_16x16x32_bf16 v[64:67], v[198:201], v[116:119], v[72:75]
	v_mfma_f32_16x16x32_bf16 v[148:151], v[202:205], v[112:115], v[120:123]
	v_mfma_f32_16x16x32_bf16 v[120:123], v[202:205], v[178:181], v[64:67]
	v_mfma_f32_16x16x32_bf16 v[64:67], v[206:209], v[116:119], v[76:79]
	v_mfma_f32_16x16x32_bf16 v[112:115], v[210:213], v[178:181], v[64:67]
	v_mfma_f32_16x16x32_bf16 v[64:67], v[198:201], v[182:185], v[80:83]
	v_mfma_f32_16x16x32_bf16 v[116:119], v[202:205], v[186:189], v[64:67]
	v_mfma_f32_16x16x32_bf16 v[64:67], v[206:209], v[182:185], v[100:103]
	v_mfma_f32_16x16x32_bf16 v[100:103], v[210:213], v[186:189], v[64:67]
	v_mfma_f32_16x16x32_bf16 v[64:67], v[198:201], v[190:193], v[136:139]
	v_mfma_f32_16x16x32_bf16 v[136:139], v[202:205], v[194:197], v[64:67]
	v_mfma_f32_16x16x32_bf16 v[64:67], v[206:209], v[190:193], v[96:99]
	v_mfma_f32_16x16x32_bf16 v[96:99], v[210:213], v[194:197], v[64:67]
	s_mov_b32 m0, s17
	s_nop 4
	v_lshl_add_u64 v[64:65], v[218:219], 0, s[52:53]
	s_barrier
	ds_read_b128 v[68:71], v237 offset:49152
	ds_read_b128 v[72:75], v237 offset:50176
	ds_read_b128 v[76:79], v237 offset:51200
	ds_read_b128 v[80:83], v237 offset:52224
	ds_read_b128 v[178:181], v237 offset:53248
	ds_read_b128 v[182:185], v237 offset:54272
	ds_read_b128 v[186:189], v237 offset:55296
	ds_read_b128 v[190:193], v237 offset:56320
	global_load_lds_dwordx4 v[64:65], off
	v_lshl_add_u64 v[64:65], v[220:221], 0, s[52:53]
	s_mov_b32 m0, s18
	s_nop 0
	global_load_lds_dwordx4 v[64:65], off
	s_barrier
	s_waitcnt lgkmcnt(0)
	s_waitcnt lgkmcnt(0)
	v_mfma_f32_16x16x32_bf16 v[64:67], v[52:55], v[68:71], v[92:95]
	v_mfma_f32_16x16x32_bf16 v[92:95], v[56:59], v[72:75], v[64:67]
	v_mfma_f32_16x16x32_bf16 v[40:43], v[84:87], v[68:71], v[40:43]
	v_mfma_f32_16x16x32_bf16 v[64:67], v[52:55], v[76:79], v[88:91]
	v_mfma_f32_16x16x32_bf16 v[36:39], v[84:87], v[76:79], v[36:39]
	v_mfma_f32_16x16x32_bf16 v[60:63], v[52:55], v[178:181], v[60:63]
	v_mfma_f32_16x16x32_bf16 v[8:11], v[84:87], v[178:181], v[8:11]
	v_mfma_f32_16x16x32_bf16 v[44:47], v[52:55], v[186:189], v[44:47]
	v_mfma_f32_16x16x32_bf16 v[16:19], v[84:87], v[186:189], v[16:19]
	v_mfma_f32_16x16x32_bf16 v[40:43], v[174:177], v[72:75], v[40:43]
	v_mfma_f32_16x16x32_bf16 v[88:91], v[56:59], v[80:83], v[64:67]
	v_mfma_f32_16x16x32_bf16 v[36:39], v[174:177], v[80:83], v[36:39]
	v_mfma_f32_16x16x32_bf16 v[60:63], v[56:59], v[182:185], v[60:63]
	v_mfma_f32_16x16x32_bf16 v[8:11], v[174:177], v[182:185], v[8:11]
	v_mfma_f32_16x16x32_bf16 v[64:67], v[56:59], v[190:193], v[44:47]
	v_mfma_f32_16x16x32_bf16 v[16:19], v[174:177], v[190:193], v[16:19]
	s_barrier
	s_add_u32 s0, s0, 0x40080
	s_addc_u32 s1, s1, 0
	s_add_i32 s60, s60, s11
	v_lshl_add_u64 v[44:45], s[0:1], 0, v[160:161]
	s_mov_b32 m0, s60
	s_nop 0
	global_load_lds_dwordx4 v[44:45], off
	v_lshl_add_u64 v[44:45], s[0:1], 0, v[162:163]
	s_add_i32 m0, s60, 0x2000
	s_nop 0
	global_load_lds_dwordx4 v[44:45], off
	s_waitcnt vmcnt(6)
	s_barrier
	v_mfma_f32_16x16x32_bf16 v[44:47], v[198:201], v[68:71], v[48:51]
	v_mfma_f32_16x16x32_bf16 v[28:31], v[206:209], v[68:71], v[28:31]
	v_mfma_f32_16x16x32_bf16 v[24:27], v[198:201], v[76:79], v[24:27]
	v_mfma_f32_16x16x32_bf16 v[12:15], v[206:209], v[76:79], v[12:15]
	v_mfma_f32_16x16x32_bf16 v[20:23], v[198:201], v[178:181], v[20:23]
	v_mfma_f32_16x16x32_bf16 v[4:7], v[206:209], v[178:181], v[4:7]
	v_mfma_f32_16x16x32_bf16 v[32:35], v[198:201], v[186:189], v[32:35]
	v_mfma_f32_16x16x32_bf16 v[0:3], v[206:209], v[186:189], v[0:3]
	v_mfma_f32_16x16x32_bf16 v[84:87], v[202:205], v[72:75], v[44:47]
	v_mfma_f32_16x16x32_bf16 v[28:31], v[210:213], v[72:75], v[28:31]
	v_mfma_f32_16x16x32_bf16 v[24:27], v[202:205], v[80:83], v[24:27]
	v_mfma_f32_16x16x32_bf16 v[12:15], v[210:213], v[80:83], v[12:15]
	v_mfma_f32_16x16x32_bf16 v[20:23], v[202:205], v[182:185], v[20:23]
	v_mfma_f32_16x16x32_bf16 v[4:7], v[210:213], v[182:185], v[4:7]
	v_mfma_f32_16x16x32_bf16 v[32:35], v[202:205], v[190:193], v[32:35]
	v_mfma_f32_16x16x32_bf16 v[0:3], v[210:213], v[190:193], v[0:3]
	s_add_i32 s59, s59, 2
	s_add_u32 vcc_lo, vcc_lo, 0x100
	s_addc_u32 vcc_hi, vcc_hi, 0
	s_add_u32 s55, s55, 0x100
	s_addc_u32 s57, s57, 0
	s_cmp_gt_u32 s59, 13
	s_barrier
	s_cbranch_scc0 .LBB0_703
	v_lshl_add_u32 v164, s84, 8, v231
	v_lshl_add_u64 v[44:45], v[164:165], 2, s[34:35]
	global_load_dword v184, v[44:45], off
	v_or_b32_e32 v182, 16, v164
	v_mov_b32_e32 v183, v165
	v_lshl_add_u64 v[44:45], v[182:183], 2, s[34:35]
	global_load_dword v186, v[44:45], off
	v_or_b32_e32 v44, 32, v164
	v_mov_b32_e32 v45, v165
	v_lshl_add_u64 v[44:45], v[44:45], 2, s[34:35]
	v_or_b32_e32 v180, 48, v164
	v_mov_b32_e32 v181, v165
	global_load_dword v200, v[44:45], off
	v_lshl_add_u64 v[44:45], v[180:181], 2, s[34:35]
	v_add_u32_e32 v178, 0x80, v164
	v_mov_b32_e32 v179, v165
	global_load_dword v185, v[44:45], off
	v_lshl_add_u64 v[44:45], v[178:179], 2, s[34:35]
	v_add_u32_e32 v174, 0x90, v164
	v_mov_b32_e32 v175, v165
	global_load_dword v183, v[44:45], off
	v_lshl_add_u64 v[44:45], v[174:175], 2, s[34:35]
	global_load_dword v181, v[44:45], off
	v_add_u32_e32 v44, 0xa0, v164
	v_mov_b32_e32 v45, v165
	v_lshl_add_u64 v[44:45], v[44:45], 2, s[34:35]
	global_load_dword v175, v[44:45], off
	v_add_u32_e32 v44, 0xb0, v164
	v_mov_b32_e32 v45, v165
	v_lshl_or_b32 v176, s88, 7, v235
	v_lshl_add_u64 v[44:45], v[44:45], 2, s[34:35]
	v_ashrrev_i32_e32 v177, 31, v176
	v_readlane_b32 s44, v254, 1
	global_load_dword v179, v[44:45], off
	v_lshlrev_b64 v[44:45], 2, v[176:177]
	v_readlane_b32 s48, v254, 5
	v_readlane_b32 s49, v254, 6
	v_readlane_b32 s50, v254, 7
	v_readlane_b32 s51, v254, 8
	v_lshl_add_u64 v[48:49], s[48:49], 0, v[44:45]
	v_lshl_add_u64 v[52:53], s[96:97], 0, v[44:45]
	v_lshl_add_u64 v[56:57], s[86:87], 0, v[44:45]
	v_lshl_add_u64 v[80:81], s[50:51], 0, v[44:45]
	global_load_dwordx4 v[44:47], v[48:49], off offset:16
	global_load_dwordx4 v[68:71], v[48:49], off
	s_nop 0
	global_load_dwordx4 v[48:51], v[52:53], off offset:16
	global_load_dwordx4 v[72:75], v[52:53], off
	s_nop 0
	global_load_dwordx4 v[52:55], v[56:57], off offset:16
	global_load_dwordx4 v[76:79], v[56:57], off
	s_nop 0
	global_load_dwordx4 v[56:59], v[80:81], off offset:16
	s_nop 0
	global_load_dwordx4 v[80:83], v[80:81], off
	v_mov_b32_e32 v191, 0
	v_mov_b32_e32 v193, 0
	v_mov_b32_e32 v196, 0
	s_lshl_b32 s3, s84, 2
	v_mov_b32_e32 v198, 0
	s_add_i32 s3, s3, s10
	v_mov_b32_e32 v197, 0
	s_mul_i32 s51, s3, 6
	v_mov_b32_e32 v199, 0
	v_readlane_b32 s45, v254, 2
	v_readlane_b32 s46, v254, 3
	v_readlane_b32 s47, v254, 4
	s_cmpk_gt_u32 s5, 0xff
	s_cbranch_scc1 .Lepi0_ffnin0
	s_barrier
.Lepi0_ffnin0:
	s_waitcnt vmcnt(0)
	v_fmamk_f32 v177, v184, 0x3a800000, v239
	v_cmp_gt_f32_e32 vcc, s33, v177
	v_mul_f32_e32 v184, 0x4b800000, v177
	s_nop 0
	v_cndmask_b32_e32 v177, v177, v184, vcc
	v_rsq_f32_e32 v177, v177
	s_nop 0
	v_mul_f32_e32 v184, 0x45800000, v177
	v_cndmask_b32_e32 v188, v177, v184, vcc
	v_fmamk_f32 v177, v186, 0x3a800000, v239
	v_cmp_gt_f32_e32 vcc, s33, v177
	v_mul_f32_e32 v184, 0x4b800000, v177
	v_pk_mul_f32 v[186:187], v[156:157], v[188:189] op_sel_hi:[1,0]
	v_cndmask_b32_e32 v177, v177, v184, vcc
	v_rsq_f32_e32 v177, v177
	v_cndmask_b32_e64 v156, v186, 0, s[38:39]
	v_pk_mul_f32 v[194:195], v[158:159], v[188:189] op_sel_hi:[1,0]
	v_mul_f32_e32 v184, 0x45800000, v177
	v_cndmask_b32_e32 v184, v177, v184, vcc
	v_mov_b32_dpp v190, v156 row_ror:1 row_mask:0xf bank_mask:0xf
	v_pk_mul_f32 v[156:157], v[152:153], v[184:185] op_sel_hi:[1,0]
	v_pk_mul_f32 v[158:159], v[154:155], v[184:185] op_sel_hi:[1,0]
	v_cndmask_b32_e64 v152, v186, v156, s[42:43]
	v_add_u32_e32 v155, s51, v234
	s_nop 0
	v_mov_b32_dpp v192, v152 row_ror:15 row_mask:0xf bank_mask:0xf
	v_cndmask_b32_e64 v152, v187, 0, s[38:39]
	s_nop 1
	v_mov_b32_dpp v191, v152 row_ror:1 row_mask:0xf bank_mask:0xf
	v_cndmask_b32_e64 v152, v187, v157, s[42:43]
	s_nop 1
	v_mov_b32_dpp v193, v152 row_ror:15 row_mask:0xf bank_mask:0xf
	v_cndmask_b32_e64 v152, v194, 0, s[38:39]
	s_nop 1
	v_mov_b32_dpp v196, v152 row_ror:1 row_mask:0xf bank_mask:0xf
	v_cndmask_b32_e64 v152, v194, v158, s[42:43]
	s_nop 1
	v_mov_b32_dpp v198, v152 row_ror:15 row_mask:0xf bank_mask:0xf
	v_cndmask_b32_e64 v152, v195, 0, s[38:39]
	s_nop 1
	v_mov_b32_dpp v197, v152 row_ror:1 row_mask:0xf bank_mask:0xf
	v_cndmask_b32_e64 v152, v195, v159, s[42:43]
	s_nop 1
	v_mov_b32_dpp v199, v152 row_ror:15 row_mask:0xf bank_mask:0xf
	s_and_saveexec_b64 s[0:1], s[70:71]
	s_cbranch_execz .LBB0_706
	v_mad_u64_u32 v[202:203], s[22:23], v155, s65, v[176:177]
	v_mov_b32_e32 v203, v165
	v_cvt_pk_bf16_f32 v152, v186, v187
	v_cvt_pk_bf16_f32 v153, v194, v195
	v_lshl_add_u64 v[202:203], v[202:203], 1, s[30:31]
	global_store_dwordx2 v[202:203], v[152:153], off

.LBB0_888:
	ds_read_b128 v[140:143], v149
	ds_read_b128 v[152:155], v149 offset:1024
	ds_read_b128 v[156:159], v149 offset:2048
	ds_read_b128 v[160:163], v149 offset:3072
	s_add_u32 s10, s2, 0x100
	s_addc_u32 s11, s3, 0
	s_cmp_eq_u32 s39, 40
	s_cselect_b32 s15, s7, s11
	s_cselect_b32 s14, s6, s10
	s_cselect_b32 s13, s5, s38
	s_cselect_b32 s12, s4, s37
	v_lshl_add_u64 v[144:145], s[2:3], 0, v[132:133]
	s_add_i32 m0, s23, 0xc000
	ds_read_b128 v[164:167], v150
	ds_read_b128 v[168:171], v150 offset:1024
	ds_read_b128 v[172:175], v150 offset:2048
	ds_read_b128 v[176:179], v150 offset:3072
	ds_read_b128 v[180:183], v150 offset:4096
	ds_read_b128 v[184:187], v150 offset:5120
	ds_read_b128 v[188:191], v150 offset:6144
	ds_read_b128 v[192:195], v150 offset:7168
	global_load_lds_dwordx4 v[144:145], off
	v_lshl_add_u64 v[144:145], s[2:3], 0, v[134:135]
	s_add_i32 m0, s23, 0xe000
	s_nop 0
	global_load_lds_dwordx4 v[144:145], off
	s_waitcnt lgkmcnt(8)
	s_barrier
	s_waitcnt lgkmcnt(0)
	s_waitcnt lgkmcnt(0)
	v_mfma_f32_16x16x32_bf16 v[124:127], v[140:143], v[164:167], v[124:127]
	v_mfma_f32_16x16x32_bf16 v[120:123], v[156:159], v[164:167], v[120:123]
	v_mfma_f32_16x16x32_bf16 v[116:119], v[140:143], v[172:175], v[116:119]
	v_mfma_f32_16x16x32_bf16 v[112:115], v[156:159], v[172:175], v[112:115]
	v_mfma_f32_16x16x32_bf16 v[92:95], v[140:143], v[180:183], v[92:95]
	v_mfma_f32_16x16x32_bf16 v[88:91], v[156:159], v[180:183], v[88:91]
	v_mfma_f32_16x16x32_bf16 v[84:87], v[140:143], v[188:191], v[84:87]
	v_mfma_f32_16x16x32_bf16 v[80:83], v[156:159], v[188:191], v[80:83]
	v_mfma_f32_16x16x32_bf16 v[124:127], v[152:155], v[168:171], v[124:127]
	v_mfma_f32_16x16x32_bf16 v[120:123], v[160:163], v[168:171], v[120:123]
	v_mfma_f32_16x16x32_bf16 v[116:119], v[152:155], v[176:179], v[116:119]
	v_mfma_f32_16x16x32_bf16 v[112:115], v[160:163], v[176:179], v[112:115]
	v_mfma_f32_16x16x32_bf16 v[92:95], v[152:155], v[184:187], v[92:95]
	v_mfma_f32_16x16x32_bf16 v[88:91], v[160:163], v[184:187], v[88:91]
	v_mfma_f32_16x16x32_bf16 v[84:87], v[152:155], v[192:195], v[84:87]
	v_mfma_f32_16x16x32_bf16 v[80:83], v[160:163], v[192:195], v[80:83]
	s_barrier
	s_add_i32 s2, s30, s22
	v_lshl_add_u64 v[144:145], s[12:13], 0, v[128:129]
	s_mov_b32 m0, s2
	ds_read_b128 v[196:199], v151
	ds_read_b128 v[200:203], v151 offset:1024
	ds_read_b128 v[204:207], v151 offset:2048
	ds_read_b128 v[208:211], v151 offset:3072
	global_load_lds_dwordx4 v[144:145], off
	v_lshl_add_u64 v[212:213], s[12:13], 0, v[130:131]
	s_add_i32 m0, s2, 0x2000
	s_nop 0
	global_load_lds_dwordx4 v[212:213], off
	s_barrier
	s_waitcnt lgkmcnt(0)
	s_waitcnt lgkmcnt(0)
	v_mfma_f32_16x16x32_bf16 v[108:111], v[196:199], v[164:167], v[108:111]
	v_mfma_f32_16x16x32_bf16 v[104:107], v[204:207], v[164:167], v[104:107]
	v_mfma_f32_16x16x32_bf16 v[100:103], v[196:199], v[172:175], v[100:103]
	v_mfma_f32_16x16x32_bf16 v[96:99], v[204:207], v[172:175], v[96:99]
	v_mfma_f32_16x16x32_bf16 v[76:79], v[196:199], v[180:183], v[76:79]
	v_mfma_f32_16x16x32_bf16 v[72:75], v[204:207], v[180:183], v[72:75]
	v_mfma_f32_16x16x32_bf16 v[68:71], v[196:199], v[188:191], v[68:71]
	v_mfma_f32_16x16x32_bf16 v[64:67], v[204:207], v[188:191], v[64:67]
	v_mfma_f32_16x16x32_bf16 v[108:111], v[200:203], v[168:171], v[108:111]
	v_mfma_f32_16x16x32_bf16 v[104:107], v[208:211], v[168:171], v[104:107]
	v_mfma_f32_16x16x32_bf16 v[100:103], v[200:203], v[176:179], v[100:103]
	v_mfma_f32_16x16x32_bf16 v[96:99], v[208:211], v[176:179], v[96:99]
	v_mfma_f32_16x16x32_bf16 v[76:79], v[200:203], v[184:187], v[76:79]
	v_mfma_f32_16x16x32_bf16 v[72:75], v[208:211], v[184:187], v[72:75]
	v_mfma_f32_16x16x32_bf16 v[68:71], v[200:203], v[192:195], v[68:71]
	v_mfma_f32_16x16x32_bf16 v[64:67], v[208:211], v[192:195], v[64:67]
	s_mov_b32 m0, s23
	v_lshl_add_u64 v[214:215], s[14:15], 0, v[128:129]
	s_barrier
	ds_read_b128 v[164:167], v150 offset:16384
	ds_read_b128 v[168:171], v150 offset:17408
	ds_read_b128 v[172:175], v150 offset:18432
	ds_read_b128 v[176:179], v150 offset:19456
	ds_read_b128 v[180:183], v150 offset:20480
	ds_read_b128 v[184:187], v150 offset:21504
	ds_read_b128 v[188:191], v150 offset:22528
	ds_read_b128 v[192:195], v150 offset:23552
	global_load_lds_dwordx4 v[214:215], off
	v_lshl_add_u64 v[216:217], s[14:15], 0, v[130:131]
	s_mov_b32 m0, s24
	s_nop 0
	global_load_lds_dwordx4 v[216:217], off
	s_barrier
	s_waitcnt lgkmcnt(0)
	s_waitcnt lgkmcnt(0)
	v_mfma_f32_16x16x32_bf16 v[60:63], v[140:143], v[164:167], v[60:63]
	v_mfma_f32_16x16x32_bf16 v[56:59], v[156:159], v[164:167], v[56:59]
	v_mfma_f32_16x16x32_bf16 v[52:55], v[140:143], v[172:175], v[52:55]
	v_mfma_f32_16x16x32_bf16 v[48:51], v[156:159], v[172:175], v[48:51]
	v_mfma_f32_16x16x32_bf16 v[28:31], v[140:143], v[180:183], v[28:31]
	v_mfma_f32_16x16x32_bf16 v[24:27], v[156:159], v[180:183], v[24:27]
	v_mfma_f32_16x16x32_bf16 v[16:19], v[140:143], v[188:191], v[16:19]
	v_mfma_f32_16x16x32_bf16 v[8:11], v[156:159], v[188:191], v[8:11]
	v_mfma_f32_16x16x32_bf16 v[60:63], v[152:155], v[168:171], v[60:63]
	v_mfma_f32_16x16x32_bf16 v[56:59], v[160:163], v[168:171], v[56:59]
	v_mfma_f32_16x16x32_bf16 v[52:55], v[152:155], v[176:179], v[52:55]
	v_mfma_f32_16x16x32_bf16 v[48:51], v[160:163], v[176:179], v[48:51]
	v_mfma_f32_16x16x32_bf16 v[28:31], v[152:155], v[184:187], v[28:31]
	v_mfma_f32_16x16x32_bf16 v[24:27], v[160:163], v[184:187], v[24:27]
	v_mfma_f32_16x16x32_bf16 v[16:19], v[152:155], v[192:195], v[16:19]
	v_mfma_f32_16x16x32_bf16 v[8:11], v[160:163], v[192:195], v[8:11]
	s_barrier
	s_add_u32 s2, s12, 0xb0000
	s_addc_u32 s3, s13, 0
	s_add_i32 s40, s31, s22
	v_lshl_add_u64 v[140:141], s[2:3], 0, v[128:129]
	s_mov_b32 m0, s40
	s_nop 0
	global_load_lds_dwordx4 v[140:141], off
	v_lshl_add_u64 v[140:141], s[2:3], 0, v[130:131]
	s_add_i32 m0, s40, 0x2000
	s_nop 0
	global_load_lds_dwordx4 v[140:141], off
	s_waitcnt vmcnt(6)
	s_barrier
	v_mfma_f32_16x16x32_bf16 v[44:47], v[196:199], v[164:167], v[44:47]
	v_mfma_f32_16x16x32_bf16 v[40:43], v[204:207], v[164:167], v[40:43]
	v_mfma_f32_16x16x32_bf16 v[36:39], v[196:199], v[172:175], v[36:39]
	v_mfma_f32_16x16x32_bf16 v[32:35], v[204:207], v[172:175], v[32:35]
	v_mfma_f32_16x16x32_bf16 v[20:23], v[196:199], v[180:183], v[20:23]
	v_mfma_f32_16x16x32_bf16 v[12:15], v[204:207], v[180:183], v[12:15]
	v_mfma_f32_16x16x32_bf16 v[4:7], v[196:199], v[188:191], v[4:7]
	v_mfma_f32_16x16x32_bf16 v[0:3], v[204:207], v[188:191], v[0:3]
	v_mfma_f32_16x16x32_bf16 v[44:47], v[200:203], v[168:171], v[44:47]
	v_mfma_f32_16x16x32_bf16 v[40:43], v[208:211], v[168:171], v[40:43]
	v_mfma_f32_16x16x32_bf16 v[36:39], v[200:203], v[176:179], v[36:39]
	v_mfma_f32_16x16x32_bf16 v[32:35], v[208:211], v[176:179], v[32:35]
	v_mfma_f32_16x16x32_bf16 v[20:23], v[200:203], v[184:187], v[20:23]
	v_mfma_f32_16x16x32_bf16 v[12:15], v[208:211], v[184:187], v[12:15]
	v_mfma_f32_16x16x32_bf16 v[4:7], v[200:203], v[192:195], v[4:7]
	v_mfma_f32_16x16x32_bf16 v[0:3], v[208:211], v[192:195], v[0:3]
	s_add_i32 s40, 0, 0x18000
	v_add_u32_e32 v160, s40, v147
	s_barrier
	ds_read_b128 v[140:143], v160
	ds_read_b128 v[152:155], v160 offset:1024
	ds_read_b128 v[156:159], v160 offset:2048
	ds_read_b128 v[160:163], v160 offset:3072
	s_add_u32 s2, s14, 0xb0000
	s_addc_u32 s3, s15, 0
	s_mov_b32 m0, s25
	v_lshl_add_u64 v[196:197], s[2:3], 0, v[128:129]
	ds_read_b128 v[164:167], v150 offset:32768
	ds_read_b128 v[168:171], v150 offset:33792
	ds_read_b128 v[172:175], v150 offset:34816
	ds_read_b128 v[176:179], v150 offset:35840
	ds_read_b128 v[180:183], v150 offset:36864
	ds_read_b128 v[184:187], v150 offset:37888
	ds_read_b128 v[188:191], v150 offset:38912
	ds_read_b128 v[192:195], v150 offset:39936
	global_load_lds_dwordx4 v[196:197], off
	v_lshl_add_u64 v[196:197], s[2:3], 0, v[130:131]
	s_mov_b32 m0, s26
	s_nop 0
	global_load_lds_dwordx4 v[196:197], off
	s_waitcnt lgkmcnt(8)
	s_barrier
	s_waitcnt lgkmcnt(0)
	s_waitcnt lgkmcnt(0)
	v_mfma_f32_16x16x32_bf16 v[124:127], v[140:143], v[164:167], v[124:127]
	v_mfma_f32_16x16x32_bf16 v[120:123], v[156:159], v[164:167], v[120:123]
	v_mfma_f32_16x16x32_bf16 v[116:119], v[140:143], v[172:175], v[116:119]
	v_mfma_f32_16x16x32_bf16 v[112:115], v[156:159], v[172:175], v[112:115]
	v_mfma_f32_16x16x32_bf16 v[92:95], v[140:143], v[180:183], v[92:95]
	v_mfma_f32_16x16x32_bf16 v[88:91], v[156:159], v[180:183], v[88:91]
	v_mfma_f32_16x16x32_bf16 v[84:87], v[140:143], v[188:191], v[84:87]
	v_mfma_f32_16x16x32_bf16 v[80:83], v[156:159], v[188:191], v[80:83]
	v_mfma_f32_16x16x32_bf16 v[124:127], v[152:155], v[168:171], v[124:127]
	v_mfma_f32_16x16x32_bf16 v[120:123], v[160:163], v[168:171], v[120:123]
	v_mfma_f32_16x16x32_bf16 v[116:119], v[152:155], v[176:179], v[116:119]
	v_mfma_f32_16x16x32_bf16 v[112:115], v[160:163], v[176:179], v[112:115]
	v_mfma_f32_16x16x32_bf16 v[92:95], v[152:155], v[184:187], v[92:95]
	v_mfma_f32_16x16x32_bf16 v[88:91], v[160:163], v[184:187], v[88:91]
	v_mfma_f32_16x16x32_bf16 v[84:87], v[152:155], v[192:195], v[84:87]
	v_mfma_f32_16x16x32_bf16 v[80:83], v[160:163], v[192:195], v[80:83]
	s_barrier
	s_add_i32 s14, 0, 0x1c000
	s_add_i32 s2, s40, s22
	v_add_u32_e32 v208, s14, v147
	v_lshl_add_u64 v[144:145], v[144:145], 0, s[8:9]
	s_mov_b32 m0, s2
	ds_read_b128 v[196:199], v208
	ds_read_b128 v[200:203], v208 offset:1024
	ds_read_b128 v[204:207], v208 offset:2048
	ds_read_b128 v[208:211], v208 offset:3072
	global_load_lds_dwordx4 v[144:145], off
	v_lshl_add_u64 v[144:145], v[212:213], 0, s[8:9]
	s_add_i32 m0, s2, 0x2000
	s_nop 0
	global_load_lds_dwordx4 v[144:145], off
	s_barrier
	s_waitcnt lgkmcnt(0)
	s_waitcnt lgkmcnt(0)
	v_mfma_f32_16x16x32_bf16 v[108:111], v[196:199], v[164:167], v[108:111]
	v_mfma_f32_16x16x32_bf16 v[104:107], v[204:207], v[164:167], v[104:107]
	v_mfma_f32_16x16x32_bf16 v[100:103], v[196:199], v[172:175], v[100:103]
	v_mfma_f32_16x16x32_bf16 v[96:99], v[204:207], v[172:175], v[96:99]
	v_mfma_f32_16x16x32_bf16 v[76:79], v[196:199], v[180:183], v[76:79]
	v_mfma_f32_16x16x32_bf16 v[72:75], v[204:207], v[180:183], v[72:75]
	v_mfma_f32_16x16x32_bf16 v[68:71], v[196:199], v[188:191], v[68:71]
	v_mfma_f32_16x16x32_bf16 v[64:67], v[204:207], v[188:191], v[64:67]
	v_mfma_f32_16x16x32_bf16 v[108:111], v[200:203], v[168:171], v[108:111]
	v_mfma_f32_16x16x32_bf16 v[104:107], v[208:211], v[168:171], v[104:107]
	v_mfma_f32_16x16x32_bf16 v[100:103], v[200:203], v[176:179], v[100:103]
	v_mfma_f32_16x16x32_bf16 v[96:99], v[208:211], v[176:179], v[96:99]
	v_mfma_f32_16x16x32_bf16 v[76:79], v[200:203], v[184:187], v[76:79]
	v_mfma_f32_16x16x32_bf16 v[72:75], v[208:211], v[184:187], v[72:75]
	v_mfma_f32_16x16x32_bf16 v[68:71], v[200:203], v[192:195], v[68:71]
	v_mfma_f32_16x16x32_bf16 v[64:67], v[208:211], v[192:195], v[64:67]
	s_mov_b32 m0, s28
	v_lshl_add_u64 v[144:145], v[214:215], 0, s[8:9]
	s_barrier
	ds_read_b128 v[164:167], v150 offset:49152
	ds_read_b128 v[168:171], v150 offset:50176
	ds_read_b128 v[172:175], v150 offset:51200
	ds_read_b128 v[176:179], v150 offset:52224
	ds_read_b128 v[180:183], v150 offset:53248
	ds_read_b128 v[184:187], v150 offset:54272
	ds_read_b128 v[188:191], v150 offset:55296
	ds_read_b128 v[192:195], v150 offset:56320
	global_load_lds_dwordx4 v[144:145], off
	v_lshl_add_u64 v[144:145], v[216:217], 0, s[8:9]
	s_mov_b32 m0, s29
	s_nop 0
	global_load_lds_dwordx4 v[144:145], off
	s_barrier
	s_waitcnt lgkmcnt(0)
	s_waitcnt lgkmcnt(0)
	v_mfma_f32_16x16x32_bf16 v[60:63], v[140:143], v[164:167], v[60:63]
	v_mfma_f32_16x16x32_bf16 v[56:59], v[156:159], v[164:167], v[56:59]
	v_mfma_f32_16x16x32_bf16 v[52:55], v[140:143], v[172:175], v[52:55]
	v_mfma_f32_16x16x32_bf16 v[48:51], v[156:159], v[172:175], v[48:51]
	v_mfma_f32_16x16x32_bf16 v[28:31], v[140:143], v[180:183], v[28:31]
	v_mfma_f32_16x16x32_bf16 v[24:27], v[156:159], v[180:183], v[24:27]
	v_mfma_f32_16x16x32_bf16 v[16:19], v[140:143], v[188:191], v[16:19]
	v_mfma_f32_16x16x32_bf16 v[8:11], v[156:159], v[188:191], v[8:11]
	v_mfma_f32_16x16x32_bf16 v[60:63], v[152:155], v[168:171], v[60:63]
	v_mfma_f32_16x16x32_bf16 v[56:59], v[160:163], v[168:171], v[56:59]
	v_mfma_f32_16x16x32_bf16 v[52:55], v[152:155], v[176:179], v[52:55]
	v_mfma_f32_16x16x32_bf16 v[48:51], v[160:163], v[176:179], v[48:51]
	v_mfma_f32_16x16x32_bf16 v[28:31], v[152:155], v[184:187], v[28:31]
	v_mfma_f32_16x16x32_bf16 v[24:27], v[160:163], v[184:187], v[24:27]
	v_mfma_f32_16x16x32_bf16 v[16:19], v[152:155], v[192:195], v[16:19]
	v_mfma_f32_16x16x32_bf16 v[8:11], v[160:163], v[192:195], v[8:11]
	s_barrier
	s_add_u32 s2, s12, 0xb0080
	s_addc_u32 s3, s13, 0
	s_add_i32 s12, s14, s22
	v_lshl_add_u64 v[140:141], s[2:3], 0, v[128:129]
	s_mov_b32 m0, s12
	s_nop 0
	global_load_lds_dwordx4 v[140:141], off
	v_lshl_add_u64 v[140:141], s[2:3], 0, v[130:131]
	s_add_i32 m0, s12, 0x2000
	s_nop 0
	global_load_lds_dwordx4 v[140:141], off
	s_waitcnt vmcnt(6)
	s_barrier
	v_mfma_f32_16x16x32_bf16 v[44:47], v[196:199], v[164:167], v[44:47]
	v_mfma_f32_16x16x32_bf16 v[40:43], v[204:207], v[164:167], v[40:43]
	v_mfma_f32_16x16x32_bf16 v[36:39], v[196:199], v[172:175], v[36:39]
	v_mfma_f32_16x16x32_bf16 v[32:35], v[204:207], v[172:175], v[32:35]
	v_mfma_f32_16x16x32_bf16 v[20:23], v[196:199], v[180:183], v[20:23]
	v_mfma_f32_16x16x32_bf16 v[12:15], v[204:207], v[180:183], v[12:15]
	v_mfma_f32_16x16x32_bf16 v[4:7], v[196:199], v[188:191], v[4:7]
	v_mfma_f32_16x16x32_bf16 v[0:3], v[204:207], v[188:191], v[0:3]
	v_mfma_f32_16x16x32_bf16 v[44:47], v[200:203], v[168:171], v[44:47]
	v_mfma_f32_16x16x32_bf16 v[40:43], v[208:211], v[168:171], v[40:43]
	v_mfma_f32_16x16x32_bf16 v[36:39], v[200:203], v[176:179], v[36:39]
	v_mfma_f32_16x16x32_bf16 v[32:35], v[208:211], v[176:179], v[32:35]
	v_mfma_f32_16x16x32_bf16 v[20:23], v[200:203], v[184:187], v[20:23]
	v_mfma_f32_16x16x32_bf16 v[12:15], v[208:211], v[184:187], v[12:15]
	v_mfma_f32_16x16x32_bf16 v[4:7], v[200:203], v[192:195], v[4:7]
	v_mfma_f32_16x16x32_bf16 v[0:3], v[208:211], v[192:195], v[0:3]
	s_add_i32 s39, s39, 2
	s_add_u32 s37, s37, 0x100
	s_addc_u32 s38, s38, 0
	s_cmp_gt_u32 s39, 41
	s_mov_b64 s[2:3], s[10:11]
	s_barrier
	s_cbranch_scc0 .LBB0_888
	v_lshl_or_b32 v140, s36, 8, v148
	v_lshl_add_u32 v144, s35, 8, v146
	v_ashrrev_i32_e32 v141, 31, v140
	v_lshlrev_b64 v[140:141], 2, v[140:141]
	v_ashrrev_i32_e32 v145, 31, v144
	v_lshl_add_u64 v[142:143], s[78:79], 0, v[140:141]
	v_lshlrev_b64 v[184:185], 12, v[144:145]
	v_lshl_add_u64 v[164:165], v[142:143], 0, v[184:185]
	v_or_b32_e32 v168, 16, v144
	global_load_dwordx4 v[152:155], v[164:165], off offset:16
	global_load_dwordx4 v[156:159], v[164:165], off
	global_load_dwordx4 v[160:163], v[164:165], off offset:144
	s_nop 0
	global_load_dwordx4 v[164:167], v[164:165], off offset:128
	v_ashrrev_i32_e32 v169, 31, v168
	v_lshlrev_b64 v[186:187], 12, v[168:169]
	v_lshl_add_u64 v[180:181], v[142:143], 0, v[186:187]
	global_load_dwordx4 v[168:171], v[180:181], off offset:16
	global_load_dwordx4 v[172:175], v[180:181], off
	global_load_dwordx4 v[176:179], v[180:181], off offset:144
	s_nop 0
	global_load_dwordx4 v[180:183], v[180:181], off offset:128
	s_and_b64 vcc, exec, s[0:1]
	s_mov_b32 s36, s34
	s_mov_b32 s35, s33
	s_mov_b64 s[10:11], s[4:5]
	s_mov_b64 s[2:3], s[6:7]
	s_cmpk_gt_u32 s16, 0xff
	s_cbranch_scc1 .Lepi0_ffnout0
	s_barrier
.Lepi0_ffnout0:
	s_waitcnt vmcnt(0)
	v_pk_add_f32 v[120:121], v[120:121], v[152:153]
	v_lshl_add_u64 v[152:153], s[78:79], 0, v[184:185]
	v_pk_add_f32 v[126:127], v[126:127], v[158:159]
	v_pk_add_f32 v[124:125], v[124:125], v[156:157]
	v_pk_add_f32 v[108:109], v[108:109], v[164:165]
	v_lshl_add_u64 v[152:153], v[152:153], 0, v[140:141]
	v_pk_add_f32 v[122:123], v[122:123], v[154:155]
	v_pk_add_f32 v[110:111], v[110:111], v[166:167]
	v_pk_add_f32 v[106:107], v[106:107], v[162:163]
	v_pk_add_f32 v[104:105], v[104:105], v[160:161]
	global_store_dwordx4 v[152:153], v[124:127], off nt
	global_store_dwordx4 v[152:153], v[120:123], off offset:16 nt
	global_store_dwordx4 v[152:153], v[108:111], off offset:128 nt
	global_store_dwordx4 v[152:153], v[104:107], off offset:144 nt
	v_pk_add_f32 v[96:97], v[96:97], v[176:177]
	v_pk_add_f32 v[108:109], v[112:113], v[168:169]
	v_lshl_add_u64 v[112:113], s[78:79], 0, v[186:187]
	v_pk_add_f32 v[106:107], v[118:119], v[174:175]
	v_pk_add_f32 v[104:105], v[116:117], v[172:173]
	v_lshl_add_u64 v[112:113], v[112:113], 0, v[140:141]
	v_pk_add_f32 v[110:111], v[114:115], v[170:171]
	v_pk_add_f32 v[102:103], v[102:103], v[182:183]
	v_pk_add_f32 v[100:101], v[100:101], v[180:181]
	v_pk_add_f32 v[98:99], v[98:99], v[178:179]
	global_store_dwordx4 v[112:113], v[104:107], off nt
	global_store_dwordx4 v[112:113], v[108:111], off offset:16 nt
	global_store_dwordx4 v[112:113], v[100:103], off offset:128 nt
	global_store_dwordx4 v[112:113], v[96:99], off offset:144 nt
	v_or_b32_e32 v112, 48, v144
	v_ashrrev_i32_e32 v113, 31, v112
	v_or_b32_e32 v96, 32, v144
	v_ashrrev_i32_e32 v97, 31, v96
	v_lshlrev_b64 v[152:153], 12, v[96:97]
	v_lshl_add_u64 v[108:109], v[142:143], 0, v[152:153]
	global_load_dwordx4 v[96:99], v[108:109], off offset:16
	global_load_dwordx4 v[100:103], v[108:109], off
	global_load_dwordx4 v[104:107], v[108:109], off offset:144
	s_nop 0
	global_load_dwordx4 v[108:111], v[108:109], off offset:128
	v_lshlrev_b64 v[154:155], 12, v[112:113]
	v_lshl_add_u64 v[124:125], v[142:143], 0, v[154:155]
	global_load_dwordx4 v[112:115], v[124:125], off offset:16
	global_load_dwordx4 v[116:119], v[124:125], off
	global_load_dwordx4 v[120:123], v[124:125], off offset:144
	s_nop 0
	global_load_dwordx4 v[124:127], v[124:125], off offset:128
	s_waitcnt vmcnt(0)
	v_pk_add_f32 v[88:89], v[88:89], v[96:97]
	v_lshl_add_u64 v[96:97], s[78:79], 0, v[152:153]
	v_pk_add_f32 v[94:95], v[94:95], v[102:103]
	v_pk_add_f32 v[92:93], v[92:93], v[100:101]
	v_pk_add_f32 v[76:77], v[76:77], v[108:109]
	v_lshl_add_u64 v[96:97], v[96:97], 0, v[140:141]
	v_pk_add_f32 v[90:91], v[90:91], v[98:99]
	v_pk_add_f32 v[78:79], v[78:79], v[110:111]
	v_pk_add_f32 v[74:75], v[74:75], v[106:107]
	v_pk_add_f32 v[72:73], v[72:73], v[104:105]
	global_store_dwordx4 v[96:97], v[92:95], off nt
	global_store_dwordx4 v[96:97], v[88:91], off offset:16 nt
	global_store_dwordx4 v[96:97], v[76:79], off offset:128 nt
	global_store_dwordx4 v[96:97], v[72:75], off offset:144 nt
	v_pk_add_f32 v[64:65], v[64:65], v[120:121]
	v_pk_add_f32 v[76:77], v[80:81], v[112:113]
	v_lshl_add_u64 v[80:81], s[78:79], 0, v[154:155]
	v_pk_add_f32 v[74:75], v[86:87], v[118:119]
	v_pk_add_f32 v[72:73], v[84:85], v[116:117]
	v_lshl_add_u64 v[80:81], v[80:81], 0, v[140:141]
	v_pk_add_f32 v[78:79], v[82:83], v[114:115]
	v_pk_add_f32 v[70:71], v[70:71], v[126:127]
	v_pk_add_f32 v[68:69], v[68:69], v[124:125]
	v_pk_add_f32 v[66:67], v[66:67], v[122:123]
	global_store_dwordx4 v[80:81], v[72:75], off nt
	global_store_dwordx4 v[80:81], v[76:79], off offset:16 nt
	global_store_dwordx4 v[80:81], v[68:71], off offset:128 nt
	global_store_dwordx4 v[80:81], v[64:67], off offset:144 nt
	s_nop 1
	v_add_u32_e32 v64, 0x80, v144
	v_ashrrev_i32_e32 v65, 31, v64
	v_lshlrev_b64 v[96:97], 12, v[64:65]
	v_lshl_add_u64 v[80:81], v[142:143], 0, v[96:97]
	global_load_dwordx4 v[64:67], v[80:81], off offset:16
	global_load_dwordx4 v[68:71], v[80:81], off
	global_load_dwordx4 v[72:75], v[80:81], off offset:144
	global_load_dwordx4 v[76:79], v[80:81], off offset:128
	v_add_u32_e32 v80, 0x90, v144
	v_ashrrev_i32_e32 v81, 31, v80
	v_lshlrev_b64 v[98:99], 12, v[80:81]
	v_lshl_add_u64 v[100:101], v[142:143], 0, v[98:99]
	global_load_dwordx4 v[80:83], v[100:101], off offset:16
	global_load_dwordx4 v[84:87], v[100:101], off
	global_load_dwordx4 v[88:91], v[100:101], off offset:144
	global_load_dwordx4 v[92:95], v[100:101], off offset:128
	s_waitcnt vmcnt(0)
	v_pk_add_f32 v[56:57], v[56:57], v[64:65]
	v_lshl_add_u64 v[64:65], s[78:79], 0, v[96:97]
	v_pk_add_f32 v[62:63], v[62:63], v[70:71]
	v_pk_add_f32 v[60:61], v[60:61], v[68:69]
	v_pk_add_f32 v[44:45], v[44:45], v[76:77]
	v_lshl_add_u64 v[64:65], v[64:65], 0, v[140:141]
	v_pk_add_f32 v[58:59], v[58:59], v[66:67]
	v_pk_add_f32 v[46:47], v[46:47], v[78:79]
	v_pk_add_f32 v[42:43], v[42:43], v[74:75]
	v_pk_add_f32 v[40:41], v[40:41], v[72:73]
	global_store_dwordx4 v[64:65], v[60:63], off nt
	global_store_dwordx4 v[64:65], v[56:59], off offset:16 nt
	global_store_dwordx4 v[64:65], v[44:47], off offset:128 nt
	global_store_dwordx4 v[64:65], v[40:43], off offset:144 nt
	v_pk_add_f32 v[32:33], v[32:33], v[88:89]
	v_pk_add_f32 v[44:45], v[48:49], v[80:81]
	v_lshl_add_u64 v[48:49], s[78:79], 0, v[98:99]
	v_pk_add_f32 v[42:43], v[54:55], v[86:87]
	v_pk_add_f32 v[40:41], v[52:53], v[84:85]
	v_lshl_add_u64 v[48:49], v[48:49], 0, v[140:141]
	v_pk_add_f32 v[46:47], v[50:51], v[82:83]
	v_pk_add_f32 v[38:39], v[38:39], v[94:95]
	v_pk_add_f32 v[36:37], v[36:37], v[92:93]
	v_pk_add_f32 v[34:35], v[34:35], v[90:91]
	global_store_dwordx4 v[48:49], v[40:43], off nt
	global_store_dwordx4 v[48:49], v[44:47], off offset:16 nt
	global_store_dwordx4 v[48:49], v[36:39], off offset:128 nt
	global_store_dwordx4 v[48:49], v[32:35], off offset:144 nt
	s_nop 1
	v_add_u32_e32 v32, 0xa0, v144
	v_ashrrev_i32_e32 v33, 31, v32
	v_lshlrev_b64 v[60:61], 12, v[32:33]
	v_lshl_add_u64 v[48:49], v[142:143], 0, v[60:61]
	global_load_dwordx4 v[40:43], v[48:49], off offset:16
	global_load_dwordx4 v[44:47], v[48:49], off
	global_load_dwordx4 v[32:35], v[48:49], off offset:144
	global_load_dwordx4 v[36:39], v[48:49], off offset:128
	v_add_u32_e32 v48, 0xb0, v144
	v_ashrrev_i32_e32 v49, 31, v48
	v_lshlrev_b64 v[62:63], 12, v[48:49]
	v_lshl_add_u64 v[68:69], v[142:143], 0, v[62:63]
	global_load_dwordx4 v[48:51], v[68:69], off offset:16
	global_load_dwordx4 v[56:59], v[68:69], off
	global_load_dwordx4 v[52:55], v[68:69], off offset:144
	global_load_dwordx4 v[64:67], v[68:69], off offset:128
	s_waitcnt vmcnt(0)
	v_pk_add_f32 v[26:27], v[26:27], v[42:43]
	v_pk_add_f32 v[30:31], v[30:31], v[46:47]
	v_pk_add_f32 v[12:13], v[12:13], v[32:33]
	v_lshl_add_u64 v[32:33], s[78:79], 0, v[60:61]
	v_pk_add_f32 v[28:29], v[28:29], v[44:45]
	v_lshl_add_u64 v[32:33], v[32:33], 0, v[140:141]
	v_pk_add_f32 v[24:25], v[24:25], v[40:41]
	v_pk_add_f32 v[22:23], v[22:23], v[38:39]
	v_pk_add_f32 v[20:21], v[20:21], v[36:37]
	v_pk_add_f32 v[14:15], v[14:15], v[34:35]
	global_store_dwordx4 v[32:33], v[28:31], off nt
	global_store_dwordx4 v[32:33], v[24:27], off offset:16 nt
	global_store_dwordx4 v[32:33], v[20:23], off offset:128 nt
	global_store_dwordx4 v[32:33], v[12:15], off offset:144 nt
	v_pk_add_f32 v[10:11], v[10:11], v[50:51]
	v_pk_add_f32 v[8:9], v[8:9], v[48:49]
	v_pk_add_f32 v[12:13], v[16:17], v[56:57]
	v_lshl_add_u64 v[16:17], s[78:79], 0, v[62:63]
	v_pk_add_f32 v[14:15], v[18:19], v[58:59]
	v_lshl_add_u64 v[16:17], v[16:17], 0, v[140:141]
	v_pk_add_f32 v[6:7], v[6:7], v[66:67]
	v_pk_add_f32 v[4:5], v[4:5], v[64:65]
	v_pk_add_f32 v[2:3], v[2:3], v[54:55]
	v_pk_add_f32 v[0:1], v[0:1], v[52:53]
	global_store_dwordx4 v[16:17], v[12:15], off nt
	global_store_dwordx4 v[16:17], v[8:11], off offset:16 nt
	global_store_dwordx4 v[16:17], v[4:7], off offset:128 nt
	global_store_dwordx4 v[16:17], v[0:3], off offset:144 nt
	s_cbranch_vccz .LBB0_877
	s_waitcnt vmcnt(0)
	s_cmpk_gt_u32 s16, 0xff
	s_cbranch_scc1 .LBB0_892
